# P6/P9 tail-round tiles split into two 128-row halves (MFMA blocks skipped, stores masked) + attention hoist + norm + ssd
# speedup vs baseline: 1.0234x; 1.0059x over previous
; __device__ __forceinline__ void attn_item(const Args& a, LAS unsigned char* lds, int layer, bool is_sample, int b, int c, int kvh, int seq_row0, int nchunks, bf16_t* proj, const int tid) {
;     const int wave = __builtin_amdgcn_readfirstlane(tid >> 6), lane = tid & 63, fr = lane & 15, fq = lane >> 4;
;     const int row0 = seq_row0 + c * 64;
;     const float* kng = a.in[21] + layer * 64;
;     u32x4 qraw[2][2];
;     {
;         const int hq_ = kvh * 4 + (wave >> 1);
; #pragma unroll
;         for (int sub = 0; sub < 2; ++sub) { const bf16_t* qp_ = proj + (size_t)(row0 + (wave & 1) * 32 + sub * 16 + fr) * PN + C_Q + hq_ * 64;
; #pragma unroll
;             for (int ks = 0; ks < 2; ++ks) qraw[sub][ks] = *(const u32x4*)(qp_ + 32 * ks + 8 * fq); }
;     }
; #pragma unroll
;     for (int i = 0; i < 3; ++i) {
;         const int slot = tid + 512 * i, kl = slot >> 3, oc = slot & 7;
;         const int pos = c * 64 - 128 + kl;
;         float kf[8], vf[8];
;         if (is_sample && kl < 128) {
;             const size_t off = (((size_t)(layer * NSB + b) * 128 + kl) * NKVH + kvh) * 64 + oc * 8;
;             const f32x4 k0 = *(const f32x4*)(a.in[2] + off), k1 = *(const f32x4*)(a.in[2] + off + 4), v0 = *(const f32x4*)(a.in[3] + off), v1 = *(const f32x4*)(a.in[3] + off + 4);
; #pragma unroll
;             for (int e = 0; e < 4; ++e) { kf[e] = k0[e]; kf[4 + e] = k1[e]; vf[e] = v0[e]; vf[4 + e] = v1[e]; }
;         } else if (pos >= 0) {
;             const bf16_t* rp = proj + (size_t)(seq_row0 + pos) * PN;
;             const u32x4 kw = *(const u32x4*)(rp + C_K + kvh * 64 + oc * 8), vw = *(const u32x4*)(rp + C_V + kvh * 64 + oc * 8);
.LBB0_454:
	s_and_b64 vcc, exec, s[4:5]
	s_cbranch_vccz .LBB0_482
	s_ashr_i32 s4, s16, 7
	v_readlane_b32 s5, v255, 38
	s_add_i32 s6, s4, s5
	v_mov_b32_e32 v36, v166
	s_lshl_b32 s4, s6, 11
	v_readlane_b32 s5, v255, 31
	s_and_b32 s7, s3, 3
	s_bfe_u32 s21, s3, 0x50002
	s_sub_i32 s43, s4, s5
	v_readfirstlane_b32 s4, v36
	v_and_b32_e32 v41, 15, v36
	s_lshl_b32 s38, s21, 6
	s_lshl_b32 s40, s7, 2
	s_ashr_i32 s20, s4, 7
	s_lshr_b32 s4, s4, 1
	s_or_b32 s23, s43, s38
	s_add_i32 s39, s20, s40
	v_and_or_b32 v92, s4, 32, v41
	v_or_b32_e32 v12, s23, v92
	s_lshl_b32 s8, s39, 6
	v_mov_b64_e32 v[10:11], s[18:19]
	s_ashr_i32 s9, s8, 31
	v_mad_i64_i32 v[2:3], s[4:5], v12, s33, v[10:11]
	v_bfe_u32 v42, v36, 4, 2
	s_lshl_b64 s[4:5], s[8:9], 1
	v_lshl_add_u64 v[2:3], v[2:3], 0, s[4:5]
	v_lshlrev_b32_e32 v0, 4, v42
	v_or_b32_e32 v12, 16, v12
	v_lshl_add_u64 v[2:3], v[2:3], 0, v[0:1]
	s_mov_b64 s[16:17], 0x2800
	s_movk_i32 s10, 0x2000
	v_mad_i64_i32 v[10:11], s[14:15], v12, s33, v[10:11]
	v_lshl_add_u64 v[6:7], v[2:3], 0, s[16:17]
	v_add_co_u32_e32 v2, vcc, s10, v2
	v_lshl_add_u64 v[10:11], v[10:11], 0, s[4:5]
	s_nop 0
	v_addc_co_u32_e32 v3, vcc, 0, v3, vcc
	v_lshl_add_u64 v[10:11], v[10:11], 0, v[0:1]
	v_lshl_add_u64 v[14:15], v[10:11], 0, s[16:17]
	v_add_co_u32_e32 v10, vcc, s10, v10
	global_load_dwordx4 v[2:5], v[2:3], off offset:2048
	s_nop 0
	global_load_dwordx4 v[6:9], v[6:7], off offset:64
	v_addc_co_u32_e32 v11, vcc, 0, v11, vcc
	global_load_dwordx4 v[10:13], v[10:11], off offset:2048
	s_nop 0
	global_load_dwordx4 v[14:17], v[14:15], off offset:64
	v_and_b32_e32 v19, 7, v36
	s_add_i32 s44, s38, 0xffffff80
	s_lshl_b32 s41, s7, 6
	v_readlane_b32 s4, v255, 14
	v_ashrrev_i32_e32 v37, 3, v36
	v_lshlrev_b32_e32 v43, 3, v19
	v_lshlrev_b32_e32 v0, 5, v19
	v_readlane_b32 s5, v255, 15
	s_cmp_lt_u32 s21, 30
	v_add_u32_e32 v40, s44, v37
	s_mov_b64 s[28:29], 0x2800
	s_movk_i32 s36, 0x2000
	v_lshl_add_u64 v[38:39], s[4:5], 0, v[0:1]
	s_cselect_b64 s[14:15], -1, 0
	s_or_b32 s42, s38, 0xfffff800
	s_ashr_i32 s7, s6, 31
	v_cmp_lt_i32_e32 vcc, -1, v40
	v_mov_b32_e32 v18, 0
	v_lshlrev_b32_e32 v0, 1, v43
	v_mov_b32_e32 v20, 0
	v_mov_b32_e32 v21, 0
	v_mov_b32_e32 v22, 0
	v_mov_b32_e32 v23, 0
	v_mov_b32_e32 v24, 0
	v_mov_b32_e32 v25, 0
	v_mov_b32_e32 v26, 0
	v_mov_b32_e32 v27, 0
	v_mov_b32_e32 v28, 0
	v_mov_b32_e32 v29, 0
	v_mov_b32_e32 v30, 0
	v_mov_b32_e32 v31, 0
	v_mov_b32_e32 v32, 0
	v_mov_b32_e32 v33, 0
	v_mov_b32_e32 v34, 0
	v_mov_b32_e32 v35, 0
	v_add_u32_e32 v244, s43, v40
	v_mov_b64_e32 v[240:241], s[18:19]
	v_mad_i64_i32 v[240:241], s[100:101], v244, s33, v[240:241]
	s_lshl_b32 s100, s41, 1
	s_mov_b32 s101, 0
	v_lshl_add_u64 v[240:241], v[240:241], 0, s[100:101]
	v_lshl_add_u64 v[240:241], v[240:241], 0, v[0:1]
	s_mov_b64 s[100:101], 0x11b000
	v_lshl_add_u64 v[242:243], v[240:241], 0, s[100:101]
	global_load_dwordx4 v[232:235], v[38:39], off
	global_load_dwordx4 v[236:239], v[38:39], off offset:16
	global_load_dwordx4 v[216:219], v[242:243], off
	global_load_dwordx4 v[220:223], v[242:243], off offset:512
	s_mov_b64 s[100:101], 0x233000
	v_lshl_add_u64 v[242:243], v[240:241], 0, s[100:101]
	global_load_dwordx4 v[224:227], v[242:243], off
	global_load_dwordx4 v[228:231], v[242:243], off offset:512
	s_and_saveexec_b64 s[16:17], vcc
	s_cbranch_execz .LBB0_459
; __device__ __forceinline__ void attn_item(const Args& a, LAS unsigned char* lds, int layer, bool is_sample, int b, int c, int kvh, int seq_row0, int nchunks, bf16_t* proj, const int tid) {
;     ...
;     for (int i = 0; i < 3; ++i) {
;         const int slot = tid + 512 * i, kl = slot >> 3, oc = slot & 7;
;         const int pos = c * 64 - 128 + kl;
;         float kf[8], vf[8];
;         if (is_sample && kl < 128) {
;             const size_t off = (((size_t)(layer * NSB + b) * 128 + kl) * NKVH + kvh) * 64 + oc * 8;
;             const f32x4 k0 = *(const f32x4*)(a.in[2] + off), k1 = *(const f32x4*)(a.in[2] + off + 4), v0 = *(const f32x4*)(a.in[3] + off), v1 = *(const f32x4*)(a.in[3] + off + 4);
; #pragma unroll
;             for (int e = 0; e < 4; ++e) { kf[e] = k0[e]; kf[4 + e] = k1[e]; vf[e] = v0[e]; vf[4 + e] = v1[e]; }
;         } else if (pos >= 0) {
;             const bf16_t* rp = proj + (size_t)(seq_row0 + pos) * PN;
;             const u32x4 kw = *(const u32x4*)(rp + C_K + kvh * 64 + oc * 8), vw = *(const u32x4*)(rp + C_V + kvh * 64 + oc * 8);
;             kf[0] = bflo(kw.x); kf[1] = bfhi(kw.x); kf[2] = bflo(kw.y); kf[3] = bfhi(kw.y); kf[4] = bflo(kw.z); kf[5] = bfhi(kw.z); kf[6] = bflo(kw.w); kf[7] = bfhi(kw.w);
;             vf[0] = bflo(vw.x); vf[1] = bfhi(vw.x); vf[2] = bflo(vw.y); vf[3] = bfhi(vw.y); vf[4] = bflo(vw.z); vf[5] = bfhi(vw.z); vf[6] = bflo(vw.w); vf[7] = bfhi(vw.w);
;             float ss = 0.f;
; #pragma unroll
;             for (int e = 0; e < 8; ++e) ss += kf[e] * kf[e];
;             ss += __shfl_xor(ss, 1); ss += __shfl_xor(ss, 2); ss += __shfl_xor(ss, 4);
;             const float rs = rsqrtf(ss * (1.f / 64.f) + EPS);
;             const f32x4 g0 = *(const f32x4*)(kng + oc * 8), g1 = *(const f32x4*)(kng + oc * 8 + 4);
; #pragma unroll
;             for (int e = 0; e < 4; ++e) { kf[e] = kf[e] * rs * g0[e]; kf[4 + e] = kf[4 + e] * rs * g1[e]; }
;             if (kl >= 128 && (is_sample || c >= nchunks - 2)) {
;                 const int orow = is_sample ? (kl - 128) : (c - (nchunks - 2)) * 64 + (kl - 128);
;                 const size_t nb_ = is_sample ? NSB : NPB; const int lr = is_sample ? DSEQ : 128;
;                 const size_t off = (((size_t)(layer * nb_ + b) * lr + orow) * NKVH + kvh) * 64 + oc * 8;
;                 float* ko = a.out + (is_sample ? O_KS : O_KP) + off; float* vo = a.out + (is_sample ? O_VS : O_VP) + off;
	v_add_u32_e32 v22, s43, v40
	v_mov_b64_e32 v[20:21], s[18:19]
	v_mad_i64_i32 v[20:21], s[4:5], v22, s33, v[20:21]
	s_lshl_b32 s10, s41, 1
	v_lshl_add_u64 v[20:21], v[20:21], 0, s[10:11]
	v_lshl_add_u64 v[20:21], v[20:21], 0, v[0:1]
	v_add_co_u32_e32 v24, vcc, 0x3000, v20
	s_movk_i32 s4, 0x7f
	s_nop 0
	v_addc_co_u32_e32 v25, vcc, 0, v21, vcc
	global_load_dwordx4 v[20:23], v[24:25], off
	s_nop 0
	global_load_dwordx4 v[24:27], v[24:25], off offset:512
	s_nop 0
	v_cmp_lt_i32_e32 vcc, v204, v203
	s_xor_b64 s[46:47], s[14:15], -1
	s_waitcnt vmcnt(1)
	v_mov_b32_e32 v28, v232
	v_mov_b32_e32 v29, v233
	v_mov_b32_e32 v30, v234
	v_mov_b32_e32 v31, v235
	v_mov_b32_e32 v32, v236
	v_mov_b32_e32 v33, v237
	v_mov_b32_e32 v34, v238
	v_mov_b32_e32 v35, v239
	v_lshlrev_b32_e32 v48, 16, v20
	v_and_b32_e32 v49, 0xffff0000, v20
	v_lshlrev_b32_e32 v50, 16, v21
	v_and_b32_e32 v51, 0xffff0000, v21
	v_pk_mul_f32 v[52:53], v[48:49], v[48:49]
	v_pk_mul_f32 v[54:55], v[50:51], v[50:51]
	v_add_f32_e32 v52, v52, v53
	v_lshlrev_b32_e32 v46, 16, v22
	v_and_b32_e32 v47, 0xffff0000, v22
	v_add_f32_e32 v52, v54, v52
	v_and_b32_e32 v44, 0xffff0000, v23
	v_lshlrev_b32_e32 v45, 16, v23
	v_pk_mul_f32 v[22:23], v[46:47], v[46:47]
	v_add_f32_e32 v52, v55, v52
	v_add_f32_e32 v22, v22, v52
	v_pk_mul_f32 v[20:21], v[44:45], v[44:45]
	v_add_f32_e32 v22, v23, v22
	v_cndmask_b32_e32 v40, v201, v204, vcc
	v_add_f32_e32 v21, v21, v22
	v_lshlrev_b32_e32 v40, 2, v40
	v_add_f32_e32 v20, v20, v21
	ds_bpermute_b32 v21, v40, v20
	v_cmp_lt_i32_e32 vcc, s4, v37
	v_cmp_lt_i32_e64 s[4:5], v205, v203
	s_and_b64 s[46:47], vcc, s[46:47]
	s_waitcnt lgkmcnt(0)
	v_add_f32_e32 v21, v20, v21
	v_cndmask_b32_e64 v22, v201, v205, s[4:5]
	v_lshlrev_b32_e32 v22, 2, v22
	ds_bpermute_b32 v22, v22, v21
	v_cmp_lt_i32_e64 s[4:5], v206, v203
	s_waitcnt lgkmcnt(0)
	v_add_f32_e32 v40, v21, v22
	v_cndmask_b32_e64 v20, v201, v206, s[4:5]
	v_lshlrev_b32_e32 v23, 2, v20
	ds_bpermute_b32 v52, v23, v40
	s_waitcnt vmcnt(0)
	v_lshlrev_b32_e32 v22, 16, v25
	v_and_b32_e32 v23, 0xffff0000, v25
	s_mov_b32 s4, 0x800000
	v_lshlrev_b32_e32 v20, 16, v24
	s_waitcnt lgkmcnt(0)
	v_add_f32_e32 v25, v40, v52
	v_fmamk_f32 v25, v25, 0x3c800000, v167
	v_mul_f32_e32 v40, 0x4b800000, v25
	v_cmp_gt_f32_e64 s[4:5], s4, v25
	v_and_b32_e32 v21, 0xffff0000, v24
	v_lshlrev_b32_e32 v24, 16, v26
	v_cndmask_b32_e64 v25, v25, v40, s[4:5]
	v_rsq_f32_e32 v40, v25
	v_and_b32_e32 v25, 0xffff0000, v26
	v_lshlrev_b32_e32 v26, 16, v27
	v_and_b32_e32 v27, 0xffff0000, v27
	v_mul_f32_e32 v52, 0x45800000, v40
	v_cndmask_b32_e64 v40, v40, v52, s[4:5]
	v_pk_mul_f32 v[48:49], v[40:41], v[48:49] op_sel_hi:[0,1]
	v_pk_mul_f32 v[46:47], v[40:41], v[46:47] op_sel_hi:[0,1]
	v_pk_mul_f32 v[50:51], v[40:41], v[50:51] op_sel_hi:[0,1]
	v_pk_mul_f32 v[44:45], v[40:41], v[44:45] op_sel_hi:[0,1]
	s_waitcnt vmcnt(1)
	v_pk_mul_f32 v[28:29], v[28:29], v[48:49]
	s_waitcnt vmcnt(0)
	v_pk_mul_f32 v[32:33], v[32:33], v[46:47]
	v_pk_mul_f32 v[30:31], v[30:31], v[50:51]
	v_pk_mul_f32 v[34:35], v[34:35], v[44:45] op_sel:[0,1] op_sel_hi:[1,0]
	s_and_saveexec_b64 s[4:5], s[46:47]
	s_cbranch_execz .LBB0_458
	s_lshl_b64 s[46:47], s[6:7], 7
	v_readlane_b32 s48, v255, 16
	v_add_u32_e32 v44, s42, v37
	v_readlane_b32 s49, v255, 17
	s_add_u32 s46, s46, s48
	s_addc_u32 s47, s47, s49
	v_ashrrev_i32_e32 v45, 31, v44
	v_lshl_add_u64 v[44:45], s[46:47], 0, v[44:45]
	v_lshlrev_b64 v[44:45], 8, v[44:45]
	v_or3_b32 v45, v45, 0, 0
	v_or3_b32 v44, v44, v43, s41
	v_readlane_b32 s46, v253, 58
	v_lshlrev_b64 v[44:45], 2, v[44:45]
	v_readlane_b32 s47, v253, 59
	s_nop 1
	v_lshl_add_u64 v[46:47], s[46:47], 0, v[44:45]
	v_readlane_b32 s46, v253, 60
	v_readlane_b32 s47, v253, 61
	s_nop 1
	v_lshl_add_u64 v[44:45], s[46:47], 0, v[44:45]
	global_store_dwordx4 v[46:47], v[28:31], off
	global_store_dwordx4 v[46:47], v[32:35], off offset:16
	global_store_dwordx4 v[44:45], v[20:23], off
	global_store_dwordx4 v[44:45], v[24:27], off offset:16

; #define LAS __attribute__((address_space(3)))
; __device__ __forceinline__ void attn_item(const Args& a, LAS unsigned char* lds, int layer, bool is_sample, int b, int c, int kvh, int seq_row0, int nchunks, bf16_t* proj, const int tid) {
;     ...
;     for (int i = 0; i < 3; ++i) {
;         const int slot = tid + 512 * i, kl = slot >> 3, oc = slot & 7;
;         const int pos = c * 64 - 128 + kl;
;         float kf[8], vf[8];
;         if (is_sample && kl < 128) {
;             const size_t off = (((size_t)(layer * NSB + b) * 128 + kl) * NKVH + kvh) * 64 + oc * 8;
;             const f32x4 k0 = *(const f32x4*)(a.in[2] + off), k1 = *(const f32x4*)(a.in[2] + off + 4), v0 = *(const f32x4*)(a.in[3] + off), v1 = *(const f32x4*)(a.in[3] + off + 4);
; #pragma unroll
;             for (int e = 0; e < 4; ++e) { kf[e] = k0[e]; kf[4 + e] = k1[e]; vf[e] = v0[e]; vf[4 + e] = v1[e]; }
;         } else if (pos >= 0) {
;             const bf16_t* rp = proj + (size_t)(seq_row0 + pos) * PN;
;             const u32x4 kw = *(const u32x4*)(rp + C_K + kvh * 64 + oc * 8), vw = *(const u32x4*)(rp + C_V + kvh * 64 + oc * 8);
;             kf[0] = bflo(kw.x); kf[1] = bfhi(kw.x); kf[2] = bflo(kw.y); kf[3] = bfhi(kw.y); kf[4] = bflo(kw.z); kf[5] = bfhi(kw.z); kf[6] = bflo(kw.w); kf[7] = bfhi(kw.w);
;             vf[0] = bflo(vw.x); vf[1] = bfhi(vw.x); vf[2] = bflo(vw.y); vf[3] = bfhi(vw.y); vf[4] = bflo(vw.z); vf[5] = bfhi(vw.z); vf[6] = bflo(vw.w); vf[7] = bfhi(vw.w);
;             float ss = 0.f;
; #pragma unroll
;             for (int e = 0; e < 8; ++e) ss += kf[e] * kf[e];
;             ss += __shfl_xor(ss, 1); ss += __shfl_xor(ss, 2); ss += __shfl_xor(ss, 4);
;             const float rs = rsqrtf(ss * (1.f / 64.f) + EPS);
;             const f32x4 g0 = *(const f32x4*)(kng + oc * 8), g1 = *(const f32x4*)(kng + oc * 8 + 4);
; #pragma unroll
;             for (int e = 0; e < 4; ++e) { kf[e] = kf[e] * rs * g0[e]; kf[4 + e] = kf[4 + e] * rs * g1[e]; }
;             if (kl >= 128 && (is_sample || c >= nchunks - 2)) {
;     ...
;         u32x4 w; w.x = pk2(kf[0], kf[1]); w.y = pk2(kf[2], kf[3]); w.z = pk2(kf[4], kf[5]); w.w = pk2(kf[6], kf[7]);
;         *(LAS u32x4*)(lds + L_KS + kl * PK + oc * 16) = w;
; #pragma unroll
;         for (int e = 0; e < 8; ++e) *(LAS bf16_t*)(lds + L_VT + (oc * 8 + e) * PV + (kl ^ (oc << 2)) * 2) = f2bf(vf[e]);
.LBB0_459:
	s_or_b64 exec, exec, s[16:17]
	v_lshl_add_u32 v40, v19, 4, 0
	v_cvt_pk_bf16_f32 v28, v28, v29
	v_cvt_pk_bf16_f32 v29, v30, v31
	v_cvt_pk_bf16_f32 v30, v32, v33
	v_mad_u64_u32 v[32:33], s[4:5], v37, s74, v[40:41]
	v_cvt_pk_bf16_f32 v31, v34, v35
	ds_write_b128 v32, v[28:31]
	v_lshlrev_b32_e32 v28, 1, v37
	v_xor_b32_e32 v28, v28, v43
	v_mul_u32_u24_e32 v34, 0xc80, v19
	v_cvt_pk_bf16_f32 v20, v20, v1
	v_add3_u32 v19, 0, v28, v34
	ds_write_b16 v19, v20 offset:27648
	v_cvt_pk_bf16_f32 v20, v21, v1
	ds_write_b16 v19, v20 offset:28048
	v_cvt_pk_bf16_f32 v20, v22, v1
	ds_write_b16 v19, v20 offset:28448
	v_cvt_pk_bf16_f32 v20, v23, v1
	ds_write_b16 v19, v20 offset:28848
	v_cvt_pk_bf16_f32 v20, v24, v1
	ds_write_b16 v19, v20 offset:29248
	v_cvt_pk_bf16_f32 v20, v25, v1
	v_add_u32_e32 v37, 0x200, v36
	ds_write_b16 v19, v20 offset:29648
	v_cvt_pk_bf16_f32 v20, v26, v1
	v_ashrrev_i32_e32 v35, 3, v37
	ds_write_b16 v19, v20 offset:30048
	v_cvt_pk_bf16_f32 v20, v27, v1
	v_add_u32_e32 v44, s44, v35
	ds_write_b16 v19, v20 offset:30448
	v_cmp_lt_i32_e32 vcc, -1, v44
	v_mov_b32_e32 v19, 0
	v_mov_b32_e32 v20, 0
	v_mov_b32_e32 v21, 0
	v_mov_b32_e32 v22, 0
	v_mov_b32_e32 v23, 0
	v_mov_b32_e32 v24, 0
	v_mov_b32_e32 v25, 0
	v_mov_b32_e32 v26, 0
	v_mov_b32_e32 v27, 0
	v_mov_b32_e32 v28, 0
	v_mov_b32_e32 v29, 0
	v_mov_b32_e32 v30, 0
	v_mov_b32_e32 v31, 0
	v_mov_b32_e32 v32, 0
	v_mov_b32_e32 v33, 0
	s_and_saveexec_b64 s[16:17], vcc
	s_cbranch_execz .LBB0_463
	v_add_u32_e32 v20, s43, v44
	v_mov_b64_e32 v[18:19], s[18:19]
	v_mad_i64_i32 v[18:19], s[4:5], v20, s33, v[18:19]
	s_lshl_b32 s10, s41, 1
	v_lshl_add_u64 v[18:19], v[18:19], 0, s[10:11]
	v_lshl_add_u64 v[18:19], v[18:19], 0, v[0:1]
	v_add_co_u32_e32 v22, vcc, 0x3000, v18
	s_movk_i32 s4, 0x7f
	s_nop 0
	v_addc_co_u32_e32 v23, vcc, 0, v19, vcc
	s_waitcnt vmcnt(2)
	v_mov_b32_e32 v18, v216
	v_mov_b32_e32 v19, v217
	v_mov_b32_e32 v20, v218
	v_mov_b32_e32 v21, v219
	v_mov_b32_e32 v22, v220
	v_mov_b32_e32 v23, v221
	v_mov_b32_e32 v24, v222
	v_mov_b32_e32 v25, v223
	v_mov_b32_e32 v26, v232
	v_mov_b32_e32 v27, v233
	v_mov_b32_e32 v28, v234
	v_mov_b32_e32 v29, v235
	v_mov_b32_e32 v30, v236
	v_mov_b32_e32 v31, v237
	v_mov_b32_e32 v32, v238
	v_mov_b32_e32 v33, v239
	v_cmp_lt_i32_e32 vcc, v204, v203
	s_xor_b64 s[46:47], s[14:15], -1
	s_waitcnt vmcnt(3)
	v_lshlrev_b32_e32 v48, 16, v18
	v_and_b32_e32 v49, 0xffff0000, v18
	v_lshlrev_b32_e32 v50, 16, v19
	v_and_b32_e32 v51, 0xffff0000, v19
	v_pk_mul_f32 v[52:53], v[48:49], v[48:49]
	v_pk_mul_f32 v[54:55], v[50:51], v[50:51]
	v_add_f32_e32 v52, v52, v53
	v_cndmask_b32_e32 v44, v201, v204, vcc
	v_lshlrev_b32_e32 v46, 16, v20
	v_and_b32_e32 v47, 0xffff0000, v20
	v_add_f32_e32 v52, v54, v52
	v_lshlrev_b32_e32 v56, 2, v44
	v_and_b32_e32 v44, 0xffff0000, v21
	v_lshlrev_b32_e32 v45, 16, v21
	v_pk_mul_f32 v[20:21], v[46:47], v[46:47]
	v_add_f32_e32 v52, v55, v52
	v_add_f32_e32 v20, v20, v52
	v_pk_mul_f32 v[18:19], v[44:45], v[44:45]
	v_add_f32_e32 v20, v21, v20
	v_add_f32_e32 v19, v19, v20
	v_add_f32_e32 v18, v18, v19
	ds_bpermute_b32 v19, v56, v18
	v_cmp_lt_i32_e32 vcc, s4, v35
	v_cmp_lt_i32_e64 s[4:5], v205, v203
	s_and_b64 s[46:47], vcc, s[46:47]
	s_waitcnt lgkmcnt(0)
	v_add_f32_e32 v19, v18, v19
	v_cndmask_b32_e64 v20, v201, v205, s[4:5]
	v_lshlrev_b32_e32 v20, 2, v20
	ds_bpermute_b32 v20, v20, v19
	v_cmp_lt_i32_e64 s[4:5], v206, v203
	s_waitcnt lgkmcnt(0)
	v_add_f32_e32 v52, v19, v20
	v_cndmask_b32_e64 v18, v201, v206, s[4:5]
	v_lshlrev_b32_e32 v21, 2, v18
	ds_bpermute_b32 v53, v21, v52
	s_waitcnt vmcnt(2)
	v_lshlrev_b32_e32 v20, 16, v23
	v_and_b32_e32 v21, 0xffff0000, v23
	s_mov_b32 s4, 0x800000
	v_lshlrev_b32_e32 v18, 16, v22
	s_waitcnt lgkmcnt(0)
	v_add_f32_e32 v23, v52, v53
	v_fmamk_f32 v23, v23, 0x3c800000, v167
	v_mul_f32_e32 v52, 0x4b800000, v23
	v_cmp_gt_f32_e64 s[4:5], s4, v23
	v_and_b32_e32 v19, 0xffff0000, v22
	v_lshlrev_b32_e32 v22, 16, v24
	v_cndmask_b32_e64 v23, v23, v52, s[4:5]
	v_rsq_f32_e32 v52, v23
	v_and_b32_e32 v23, 0xffff0000, v24
	v_lshlrev_b32_e32 v24, 16, v25
	v_and_b32_e32 v25, 0xffff0000, v25
	v_mul_f32_e32 v53, 0x45800000, v52
	v_cndmask_b32_e64 v52, v52, v53, s[4:5]
	v_pk_mul_f32 v[48:49], v[52:53], v[48:49] op_sel_hi:[0,1]
	v_pk_mul_f32 v[46:47], v[52:53], v[46:47] op_sel_hi:[0,1]
	v_pk_mul_f32 v[50:51], v[52:53], v[50:51] op_sel_hi:[0,1]
	v_pk_mul_f32 v[44:45], v[52:53], v[44:45] op_sel_hi:[0,1]
	s_waitcnt vmcnt(1)
	v_pk_mul_f32 v[26:27], v[26:27], v[48:49]
	s_waitcnt vmcnt(0)
	v_pk_mul_f32 v[30:31], v[30:31], v[46:47]
	v_pk_mul_f32 v[28:29], v[28:29], v[50:51]
	v_pk_mul_f32 v[32:33], v[32:33], v[44:45] op_sel:[0,1] op_sel_hi:[1,0]
	s_and_saveexec_b64 s[4:5], s[46:47]
	s_cbranch_execz .LBB0_462
	s_lshl_b64 s[46:47], s[6:7], 7
	v_readlane_b32 s48, v255, 16
	v_add_u32_e32 v44, s42, v35
	v_readlane_b32 s49, v255, 17
	s_add_u32 s46, s46, s48
	s_addc_u32 s47, s47, s49
	v_ashrrev_i32_e32 v45, 31, v44
	v_lshl_add_u64 v[44:45], s[46:47], 0, v[44:45]
	v_lshlrev_b64 v[44:45], 8, v[44:45]
	v_or3_b32 v45, v45, 0, 0
	v_or3_b32 v44, v44, v43, s41
	v_readlane_b32 s46, v253, 58
	v_lshlrev_b64 v[44:45], 2, v[44:45]
	v_readlane_b32 s47, v253, 59
	s_nop 1
	v_lshl_add_u64 v[46:47], s[46:47], 0, v[44:45]
	v_readlane_b32 s46, v253, 60
	v_readlane_b32 s47, v253, 61
	s_nop 1
	v_lshl_add_u64 v[44:45], s[46:47], 0, v[44:45]
	global_store_dwordx4 v[46:47], v[26:29], off
	global_store_dwordx4 v[46:47], v[30:33], off offset:16
	global_store_dwordx4 v[44:45], v[18:21], off
	global_store_dwordx4 v[44:45], v[22:25], off offset:16

; #define LAS __attribute__((address_space(3)))
; __device__ __forceinline__ void attn_item(const Args& a, LAS unsigned char* lds, int layer, bool is_sample, int b, int c, int kvh, int seq_row0, int nchunks, bf16_t* proj, const int tid) {
;     ...
;     for (int i = 0; i < 3; ++i) {
;         const int slot = tid + 512 * i, kl = slot >> 3, oc = slot & 7;
;         const int pos = c * 64 - 128 + kl;
;         float kf[8], vf[8];
;         if (is_sample && kl < 128) {
;             const size_t off = (((size_t)(layer * NSB + b) * 128 + kl) * NKVH + kvh) * 64 + oc * 8;
;             const f32x4 k0 = *(const f32x4*)(a.in[2] + off), k1 = *(const f32x4*)(a.in[2] + off + 4), v0 = *(const f32x4*)(a.in[3] + off), v1 = *(const f32x4*)(a.in[3] + off + 4);
; #pragma unroll
;             for (int e = 0; e < 4; ++e) { kf[e] = k0[e]; kf[4 + e] = k1[e]; vf[e] = v0[e]; vf[4 + e] = v1[e]; }
;         } else if (pos >= 0) {
;             const bf16_t* rp = proj + (size_t)(seq_row0 + pos) * PN;
;             const u32x4 kw = *(const u32x4*)(rp + C_K + kvh * 64 + oc * 8), vw = *(const u32x4*)(rp + C_V + kvh * 64 + oc * 8);
;             kf[0] = bflo(kw.x); kf[1] = bfhi(kw.x); kf[2] = bflo(kw.y); kf[3] = bfhi(kw.y); kf[4] = bflo(kw.z); kf[5] = bfhi(kw.z); kf[6] = bflo(kw.w); kf[7] = bfhi(kw.w);
;             vf[0] = bflo(vw.x); vf[1] = bfhi(vw.x); vf[2] = bflo(vw.y); vf[3] = bfhi(vw.y); vf[4] = bflo(vw.z); vf[5] = bfhi(vw.z); vf[6] = bflo(vw.w); vf[7] = bfhi(vw.w);
;             float ss = 0.f;
; #pragma unroll
;             for (int e = 0; e < 8; ++e) ss += kf[e] * kf[e];
;             ss += __shfl_xor(ss, 1); ss += __shfl_xor(ss, 2); ss += __shfl_xor(ss, 4);
;             const float rs = rsqrtf(ss * (1.f / 64.f) + EPS);
;             const f32x4 g0 = *(const f32x4*)(kng + oc * 8), g1 = *(const f32x4*)(kng + oc * 8 + 4);
; #pragma unroll
;             for (int e = 0; e < 4; ++e) { kf[e] = kf[e] * rs * g0[e]; kf[4 + e] = kf[4 + e] * rs * g1[e]; }
;             if (kl >= 128 && (is_sample || c >= nchunks - 2)) {
;     ...
;         u32x4 w; w.x = pk2(kf[0], kf[1]); w.y = pk2(kf[2], kf[3]); w.z = pk2(kf[4], kf[5]); w.w = pk2(kf[6], kf[7]);
;         *(LAS u32x4*)(lds + L_KS + kl * PK + oc * 16) = w;
; #pragma unroll
;         for (int e = 0; e < 8; ++e) *(LAS bf16_t*)(lds + L_VT + (oc * 8 + e) * PV + (kl ^ (oc << 2)) * 2) = f2bf(vf[e]);
.LBB0_463:
	s_or_b64 exec, exec, s[16:17]
	v_cvt_pk_bf16_f32 v26, v26, v27
	v_cvt_pk_bf16_f32 v27, v28, v29
	v_cvt_pk_bf16_f32 v28, v30, v31
	v_mad_u64_u32 v[30:31], s[4:5], v35, s74, v[40:41]
	v_cvt_pk_bf16_f32 v29, v32, v33
	ds_write_b128 v30, v[26:29]
	v_lshlrev_b32_e32 v26, 1, v35
	v_xor_b32_e32 v26, v26, v43
	v_cvt_pk_bf16_f32 v18, v18, v1
	v_add3_u32 v26, 0, v26, v34
	ds_write_b16 v26, v18 offset:27648
	v_cvt_pk_bf16_f32 v18, v19, v1
	ds_write_b16 v26, v18 offset:28048
	v_cvt_pk_bf16_f32 v18, v20, v1
	ds_write_b16 v26, v18 offset:28448
	v_cvt_pk_bf16_f32 v18, v21, v1
	ds_write_b16 v26, v18 offset:28848
	v_cvt_pk_bf16_f32 v18, v22, v1
	ds_write_b16 v26, v18 offset:29248
	v_cvt_pk_bf16_f32 v18, v23, v1
	ds_write_b16 v26, v18 offset:29648
	v_cvt_pk_bf16_f32 v18, v24, v1
	ds_write_b16 v26, v18 offset:30048
	v_cvt_pk_bf16_f32 v18, v25, v1
	ds_write_b16 v26, v18 offset:30448
	v_add_u32_e32 v18, 0x400, v36
	v_ashrrev_i32_e32 v35, 3, v18
	v_add_u32_e32 v44, s44, v35
	v_mov_b32_e32 v18, 0
	v_cmp_lt_i32_e32 vcc, -1, v44
	v_mov_b32_e32 v19, 0
	v_mov_b32_e32 v20, 0
	v_mov_b32_e32 v21, 0
	v_mov_b32_e32 v22, 0
	v_mov_b32_e32 v23, 0
	v_mov_b32_e32 v24, 0
	v_mov_b32_e32 v25, 0
	v_mov_b32_e32 v26, 0
	v_mov_b32_e32 v27, v18
	v_mov_b32_e32 v28, 0
	v_mov_b32_e32 v29, v18
	v_mov_b32_e32 v30, 0
	v_mov_b32_e32 v31, v18
	v_mov_b32_e32 v32, 0
	v_mov_b32_e32 v33, v18
	s_and_saveexec_b64 s[16:17], vcc
	s_cbranch_execz .LBB0_467
	v_add_u32_e32 v20, s43, v44
	v_mov_b64_e32 v[18:19], s[18:19]
	v_mad_i64_i32 v[18:19], s[4:5], v20, s33, v[18:19]
	s_lshl_b32 s10, s41, 1
	v_lshl_add_u64 v[18:19], v[18:19], 0, s[10:11]
	v_lshl_add_u64 v[18:19], v[18:19], 0, v[0:1]
	v_add_co_u32_e32 v22, vcc, 0x3000, v18
	s_movk_i32 s4, 0x7f
	s_nop 0
	v_addc_co_u32_e32 v23, vcc, 0, v19, vcc
	s_waitcnt vmcnt(0)
	v_mov_b32_e32 v18, v224
	v_mov_b32_e32 v19, v225
	v_mov_b32_e32 v20, v226
	v_mov_b32_e32 v21, v227
	v_mov_b32_e32 v22, v228
	v_mov_b32_e32 v23, v229
	v_mov_b32_e32 v24, v230
	v_mov_b32_e32 v25, v231
	v_mov_b32_e32 v26, v232
	v_mov_b32_e32 v27, v233
	v_mov_b32_e32 v28, v234
	v_mov_b32_e32 v29, v235
	v_mov_b32_e32 v30, v236
	v_mov_b32_e32 v31, v237
	v_mov_b32_e32 v32, v238
	v_mov_b32_e32 v33, v239
	v_cmp_lt_i32_e32 vcc, v204, v203
	s_xor_b64 s[14:15], s[14:15], -1
	s_waitcnt vmcnt(3)
	v_lshlrev_b32_e32 v46, 16, v18
	v_and_b32_e32 v47, 0xffff0000, v18
	v_lshlrev_b32_e32 v48, 16, v19
	v_and_b32_e32 v49, 0xffff0000, v19
	v_pk_mul_f32 v[50:51], v[46:47], v[46:47]
	v_pk_mul_f32 v[52:53], v[48:49], v[48:49]
	v_add_f32_e32 v50, v50, v51
	v_lshlrev_b32_e32 v44, 16, v20
	v_and_b32_e32 v45, 0xffff0000, v20
	v_add_f32_e32 v50, v52, v50
	v_and_b32_e32 v38, 0xffff0000, v21
	v_lshlrev_b32_e32 v39, 16, v21
	v_pk_mul_f32 v[20:21], v[44:45], v[44:45]
	v_add_f32_e32 v50, v53, v50
	v_add_f32_e32 v20, v20, v50
	v_pk_mul_f32 v[18:19], v[38:39], v[38:39]
	v_add_f32_e32 v20, v21, v20
	v_cndmask_b32_e32 v0, v201, v204, vcc
	v_add_f32_e32 v19, v19, v20
	v_lshlrev_b32_e32 v0, 2, v0
	v_add_f32_e32 v18, v18, v19
	ds_bpermute_b32 v0, v0, v18
	v_cmp_lt_i32_e32 vcc, s4, v35
	v_cmp_lt_i32_e64 s[4:5], v205, v203
	s_waitcnt vmcnt(2)
	v_and_b32_e32 v21, 0xffff0000, v23
	s_and_b64 s[14:15], vcc, s[14:15]
	v_cndmask_b32_e64 v19, v201, v205, s[4:5]
	v_lshlrev_b32_e32 v19, 2, v19
	s_waitcnt lgkmcnt(0)
	v_add_f32_e32 v0, v18, v0
	ds_bpermute_b32 v19, v19, v0
	v_cmp_lt_i32_e64 s[4:5], v206, v203
	s_waitcnt lgkmcnt(0)
	v_add_f32_e32 v0, v0, v19
	v_cndmask_b32_e64 v18, v201, v206, s[4:5]
	v_lshlrev_b32_e32 v20, 2, v18
	ds_bpermute_b32 v50, v20, v0
	s_mov_b32 s4, 0x800000
	v_lshlrev_b32_e32 v20, 16, v23
	v_lshlrev_b32_e32 v18, 16, v22
	v_and_b32_e32 v19, 0xffff0000, v22
	s_waitcnt lgkmcnt(0)
	v_add_f32_e32 v0, v0, v50
	v_fmamk_f32 v0, v0, 0x3c800000, v167
	v_mul_f32_e32 v23, 0x4b800000, v0
	v_cmp_gt_f32_e64 s[4:5], s4, v0
	v_lshlrev_b32_e32 v22, 16, v24
	s_nop 0
	v_cndmask_b32_e64 v0, v0, v23, s[4:5]
	v_rsq_f32_e32 v0, v0
	v_and_b32_e32 v23, 0xffff0000, v24
	v_lshlrev_b32_e32 v24, 16, v25
	v_and_b32_e32 v25, 0xffff0000, v25
	v_mul_f32_e32 v50, 0x45800000, v0
	v_cndmask_b32_e64 v0, v0, v50, s[4:5]
	v_pk_mul_f32 v[46:47], v[0:1], v[46:47] op_sel_hi:[0,1]
	v_pk_mul_f32 v[44:45], v[0:1], v[44:45] op_sel_hi:[0,1]
	v_pk_mul_f32 v[48:49], v[0:1], v[48:49] op_sel_hi:[0,1]
	v_pk_mul_f32 v[38:39], v[0:1], v[38:39] op_sel_hi:[0,1]
	s_waitcnt vmcnt(1)
	v_pk_mul_f32 v[26:27], v[26:27], v[46:47]
	s_waitcnt vmcnt(0)
	v_pk_mul_f32 v[30:31], v[30:31], v[44:45]
	v_pk_mul_f32 v[28:29], v[28:29], v[48:49]
	v_pk_mul_f32 v[32:33], v[32:33], v[38:39] op_sel:[0,1] op_sel_hi:[1,0]
	s_and_saveexec_b64 s[4:5], s[14:15]
	s_cbranch_execz .LBB0_466
	s_lshl_b64 s[6:7], s[6:7], 7
	v_readlane_b32 s14, v255, 16
	v_add_u32_e32 v38, s42, v35
	v_readlane_b32 s15, v255, 17
	s_add_u32 s6, s6, s14
	s_addc_u32 s7, s7, s15
	v_ashrrev_i32_e32 v39, 31, v38
	v_lshl_add_u64 v[38:39], s[6:7], 0, v[38:39]
	v_lshlrev_b64 v[38:39], 8, v[38:39]
	v_or3_b32 v39, v39, 0, 0
	v_or3_b32 v38, v38, v43, s41
	v_readlane_b32 s6, v253, 58
	v_lshlrev_b64 v[38:39], 2, v[38:39]
	v_readlane_b32 s7, v253, 59
	s_nop 1
	v_lshl_add_u64 v[44:45], s[6:7], 0, v[38:39]
	v_readlane_b32 s6, v253, 60
	v_readlane_b32 s7, v253, 61
	s_nop 1
	v_lshl_add_u64 v[38:39], s[6:7], 0, v[38:39]
	global_store_dwordx4 v[44:45], v[26:29], off
	global_store_dwordx4 v[44:45], v[30:33], off offset:16
	global_store_dwordx4 v[38:39], v[18:21], off
	global_store_dwordx4 v[38:39], v[22:25], off offset:16

;     __device__ __forceinline__ const char* Ap(int part) const { return (const char*)A0 + (long)(part == 1) * ((const char*)A1 - (const char*)A0) + (long)(part == 2) * ((const char*)A2 - (const char*)A0); }
;     __device__ __forceinline__ const char* Bp(int part) const { return (const char*)B0 + (long)(part == 1) * ((const char*)B1 - (const char*)B0) + (long)(part == 2) * ((const char*)B2 - (const char*)B0); }
; #define PG8_WAIT_V(n) asm volatile("s_waitcnt vmcnt(" #n ")" ::: "memory")
; template <class Epi, bool GS = false>
; __device__ __forceinline__ void gemm_phase(LAS unsigned char* lds, const Gemm g, const StaticOrder& S, const Epi& E, const int tid) {
;     const int wid = __builtin_amdgcn_readfirstlane(tid >> 6), lane = tid & 63, wr = wid >> 2, wc = wid & 3, fr = lane & 15, fq = lane >> 4;
;     unsigned voffA[2], voffB[2];
; #pragma unroll
;     for (int i = 0; i < 2; ++i) { int R, C; stage_rc(tid * 16 + i * 8192, R, C); const int Rb = Epi::PERM ? ((R & ~31) + perm32(R & 31)) : R;
;         voffA[i] = (unsigned)(R * g.lda + C) * 2u; voffB[i] = (unsigned)(Rb * g.ldb + C) * 2u; }
;     const size_t kstep = (size_t)(BK * 2);
;     const size_t hstepA = (size_t)HALF * g.lda * 2, hstepB = (size_t)HALF * g.ldb * 2;
;     const size_t tstepA = 2 * hstepA, tstepB = 2 * hstepB;
;     const unsigned ldsw = (unsigned)wid * 1024u;
;     const int aoff = lds_byte(wr * 64 + fr, fq * 8), boff = lds_byte(wc * 32 + fr, fq * 8);
;     ...
;     Unit cur, nxt; int ui = 0;
;     if (!S.next(0, cur)) return;
;     f32x4 acc[2][2][4][2];
; #pragma unroll
;     for (int a = 0; a < 2; ++a)
; #pragma unroll
;         for (int b = 0; b < 2; ++b)
; #pragma unroll
;             for (int m = 0; m < 4; ++m)
; #pragma unroll
;                 for (int n = 0; n < 2; ++n) acc[a][b][m][n] = (f32x4){0.f, 0.f, 0.f, 0.f};
;     bf16x8 At[4][2], B0[2][2], B1[2][2];
;     const char* cA = g.Ap(cur.part) + (size_t)cur.pm * tstepA; const char* cB = g.Bp(cur.part) + (size_t)cur.pn * tstepB;
;     PG8_STAGE(PG8_SB(0, 0), cB, voffB); PG8_STAGE(PG8_SB(0, 1), cB + hstepB, voffB); PG8_STAGE(PG8_SA(0, 0), cA, voffA); PG8_STAGE(PG8_SA(0, 1), cA + hstepA, voffA);
;     if (wr == 1) PG8_BAR;
;     PG8_WAIT_V(2); PG8_BAR;
;     PG8_STAGE(PG8_SB(1, 0), cB + kstep, voffB); PG8_STAGE(PG8_SA(1, 0), cA + kstep, voffA); PG8_STAGE(PG8_SB(1, 1), cB + hstepB + kstep, voffB);
;     PG8_WAIT_V(6); PG8_BAR;
.LBB0_772:
	s_or_b64 exec, exec, s[4:5]
	v_mov_b32_e32 v15, v166
	s_waitcnt lgkmcnt(0)
	s_barrier
	s_and_b64 vcc, exec, s[38:39]
	v_readfirstlane_b32 s4, v15
	s_cbranch_vccnz .LBB0_804
	s_mov_b32 s100, 0
	s_mov_b32 s101, 0
	v_lshlrev_b32_e32 v2, 4, v15
	v_add_u32_e32 v3, 0x2000, v2
	v_ashrrev_i32_e32 v0, 31, v3
	v_lshrrev_b32_e32 v0, 22, v0
	v_add_u32_e32 v0, v3, v0
	v_ashrrev_i32_e32 v0, 10, v0
	v_mul_i32_i24_e32 v5, 0x400, v0
	v_sub_u32_e32 v3, v3, v5
	v_lshrrev_b32_e32 v5, 4, v3
	v_bitop3_b32 v3, v5, v3, 32 bitop3:0x6c
	v_ashrrev_i32_e32 v5, 31, v3
	v_lshrrev_b32_e32 v5, 26, v5
	v_add_u32_e32 v5, v3, v5
	v_ashrrev_i32_e32 v10, 6, v5
	v_and_b32_e32 v5, 0xc0, v5
	v_sub_u32_e32 v3, v3, v5
	v_lshlrev_b32_e32 v4, 5, v0
	v_ashrrev_i16_sdwa v3, v196, sext(v3) dst_sel:DWORD dst_unused:UNUSED_PAD src0_sel:DWORD src1_sel:BYTE_0
	v_and_b32_e32 v4, 32, v4
	v_bfe_i32 v11, v3, 0, 16
	v_add_u32_e32 v3, v4, v11
	v_lshlrev_b32_e32 v4, 3, v0
	v_and_b32_e32 v4, 0x1ffff0, v4
	v_add_lshl_u32 v4, v10, v4, 11
	v_lshl_add_u32 v162, v3, 1, v4
	v_bfe_i32 v4, v15, 27, 1
	v_readlane_b32 s3, v255, 32
	v_lshrrev_b32_e32 v4, 22, v4
	s_lshr_b32 s3, s3, 9
	v_readlane_b32 s6, v254, 4
	v_add_u32_e32 v4, v2, v4
	s_or_b32 s6, s3, s6
	v_readlane_b32 s7, v254, 14
	v_and_b32_e32 v4, 0xfffffc00, v4
	s_mul_i32 s6, s6, s7
	v_readlane_b32 s7, v254, 15
	v_sub_u32_e32 v2, v2, v4
	s_add_i32 s6, s6, s7
	v_lshrrev_b32_e32 v4, 4, v2
	s_ashr_i32 s7, s6, 31
	v_bitop3_b32 v2, v4, v2, 32 bitop3:0x6c
	s_lshr_b32 s7, s7, 27
	v_ashrrev_i32_e32 v4, 31, v2
	s_add_i32 s7, s6, s7
	v_ashrrev_i32_e32 v3, 31, v15
	v_lshrrev_b32_e32 v4, 26, v4
	s_ashr_i32 s9, s7, 5
	v_lshrrev_b32_e32 v3, 26, v3
	v_add_u32_e32 v4, v2, v4
	s_lshl_b32 s9, s9, 3
	v_readlane_b32 s14, v255, 35
	v_add_u32_e32 v3, v15, v3
	v_ashrrev_i32_e32 v13, 6, v4
	v_and_b32_e32 v4, 0xc0, v4
	s_sub_i32 s14, s14, s9
	v_ashrrev_i32_e32 v12, 6, v3
	v_sub_u32_e32 v2, v2, v4
	s_min_i32 s14, s14, 8
	v_lshlrev_b32_e32 v3, 5, v12
	v_ashrrev_i16_sdwa v2, v196, sext(v2) dst_sel:DWORD dst_unused:UNUSED_PAD src0_sel:DWORD src1_sel:BYTE_0
	s_abs_i32 s15, s14
	v_and_b32_e32 v3, 32, v3
	v_bfe_i32 v14, v2, 0, 16
	v_cvt_f32_u32_e32 v4, s15
	v_add_u32_e32 v2, v3, v14
	v_lshlrev_b32_e32 v3, 3, v12
	v_and_b32_e32 v3, 0x1ffff0, v3
	v_add_lshl_u32 v3, v13, v3, 11
	v_lshl_add_u32 v164, v2, 1, v3
	v_rcp_iflag_f32_e32 v2, v4
	s_sub_i32 s17, 0, s15
	s_andn2_b32 s7, s7, 31
	s_sub_i32 s6, s6, s7
	v_mul_f32_e32 v2, 0x4f7ffffe, v2
	v_cvt_u32_f32_e32 v2, v2
	s_abs_i32 s16, s6
	s_ashr_i32 s5, s4, 6
	s_xor_b32 s7, s6, s14
	v_readfirstlane_b32 s20, v2
	s_mul_i32 s17, s17, s20
	s_mul_hi_u32 s17, s20, s17
	s_add_i32 s20, s20, s17
	s_mul_hi_u32 s17, s16, s20
	s_mul_i32 s20, s17, s15
	s_sub_i32 s16, s16, s20
	s_ashr_i32 s8, s4, 8
	s_lshl_b32 s2, s5, 10
	s_ashr_i32 s7, s7, 31
	s_add_i32 s20, s17, 1
	s_sub_i32 s21, s16, s15
	s_cmp_ge_u32 s16, s15
	s_cselect_b32 s17, s20, s17
	s_cselect_b32 s16, s21, s16
	s_add_i32 s20, s17, 1
	s_cmp_ge_u32 s16, s15
	s_cselect_b32 s15, s20, s17
	s_xor_b32 s15, s15, s7
	s_sub_i32 s40, s15, s7
	s_mul_i32 s7, s40, s14
	s_sub_i32 s6, s6, s7
	s_add_i32 s38, s6, s9
	s_ashr_i32 s39, s38, 31
	s_ashr_i32 s41, s40, 31
	s_lshl_b64 s[6:7], s[38:39], 19
	s_lshl_b64 s[14:15], s[40:41], 19
	v_readlane_b32 s9, v255, 21
	s_add_u32 s44, s9, s14
	v_readlane_b32 s9, v255, 23
	s_addc_u32 s45, s9, s15
	s_add_i32 s37, s2, 0
	s_add_i32 m0, s37, 0x10000
	v_mov_b32_e32 v165, v1
	global_load_lds_dwordx4 v164, s[44:45]
	s_add_i32 m0, s37, 0x12000
	s_add_u32 s14, s44, 0x40000
	global_load_lds_dwordx4 v162, s[44:45]
	s_addc_u32 s15, s45, 0
	s_add_i32 m0, s37, 0x14000
	v_mov_b32_e32 v163, v1
	global_load_lds_dwordx4 v164, s[14:15]
	s_add_i32 m0, s37, 0x16000
	s_add_u32 s42, s12, s6
	s_addc_u32 s43, s13, s7
	s_add_i32 s41, s37, 0x2000
	global_load_lds_dwordx4 v162, s[14:15]
	s_mov_b32 m0, s37
	s_add_u32 s6, s42, 0x40000
	global_load_lds_dwordx4 v164, s[42:43]
	s_mov_b32 m0, s41
	s_addc_u32 s7, s43, 0
	s_add_i32 s48, s37, 0x4000
	global_load_lds_dwordx4 v162, s[42:43]
	s_mov_b32 m0, s48
	s_add_i32 s49, s37, 0x6000
	global_load_lds_dwordx4 v164, s[6:7]
	s_mov_b32 m0, s49
	s_cmp_eq_u32 s8, 1
	global_load_lds_dwordx4 v162, s[6:7]
	v_lshl_add_u64 v[8:9], s[44:45], 0, v[164:165]
	v_lshl_add_u64 v[6:7], s[44:45], 0, v[162:163]
	v_lshl_add_u64 v[2:3], s[42:43], 0, v[164:165]
	s_cselect_b64 s[6:7], -1, 0
	s_cmp_lg_u32 s8, 1
	v_lshl_add_u64 v[4:5], s[42:43], 0, v[162:163]
	s_cbranch_scc1 .LBB0_775
	s_barrier

;     __device__ __forceinline__ const char* Ap(int part) const { return (const char*)A0 + (long)(part == 1) * ((const char*)A1 - (const char*)A0) + (long)(part == 2) * ((const char*)A2 - (const char*)A0); }
;     __device__ __forceinline__ const char* Bp(int part) const { return (const char*)B0 + (long)(part == 1) * ((const char*)B1 - (const char*)B0) + (long)(part == 2) * ((const char*)B2 - (const char*)B0); }
;     __device__ __forceinline__ bool next(int i, Unit& u) const {
;         const int r = i / np; u.part = i - r * np;
;         long L = (long)r * G + c;
;         if (L >= split_from) { const long Ls = L - split_from; if (Ls >= 2L * (nwg - split_from)) return false; L = split_from + (Ls >> 1); u.part = 1 + (int)(Ls & 1); }
;         if (L >= nwg) return false;
;         int wgid = (int)L; { const int q = nwg / NXCD, rr = nwg % NXCD, xcd = wgid % NXCD, off = wgid / NXCD; wgid = (xcd < rr ? xcd * (q + 1) : rr * (q + 1) + (xcd - rr) * q) + off; }
;         const int nig = WGM * nN, gid = wgid / nig, fm = gid * WGM, gsz = (nM - fm) < WGM ? (nM - fm) : WGM;
;         u.pm = fm + ((wgid % nig) % gsz); u.pn = (wgid % nig) / gsz; return true;
;     }
; template <class Epi, bool GS = false>
; __device__ __forceinline__ void gemm_phase(LAS unsigned char* lds, const Gemm g, const StaticOrder& S, const Epi& E, const int tid) {
;     ...
;         const bool has_next = S.next(ui + 1, nxt);
;         const char* nA = has_next ? g.Ap(nxt.part) + (size_t)nxt.pm * tstepA : cA; const char* nB = has_next ? g.Bp(nxt.part) + (size_t)nxt.pn * tstepB : cB;
.LBB0_777:
	s_mov_b32 s100, s101
	s_andn2_b64 vcc, exec, s[4:5]
	s_mov_b32 s40, s14
	s_mov_b32 s38, s16
	s_mov_b64 s[44:45], s[22:23]
	s_mov_b64 s[42:43], s[20:21]
	s_cbranch_vccz .LBB0_803
.LBB0_778:
	s_add_i32 s53, s53, 1
	v_readlane_b32 s4, v253, 53
	v_readlane_b32 s20, v252, 0
	s_mul_i32 s4, s53, s4
	v_readlane_b32 s21, v252, 1
	s_mul_hi_u32 s5, s53, s20
	s_add_i32 s5, s5, s4
	s_mul_i32 s4, s53, s20
	v_readlane_b32 s20, v254, 38
	v_readlane_b32 s21, v254, 39
	s_add_u32 s20, s4, s20
	s_addc_u32 s21, s5, s21
	s_mov_b32 s101, 0
	s_cmp_lt_u32 s20, 0x100
	s_cbranch_scc1 .Ltail6_ns
	s_sub_i32 s4, s20, 0x100
	s_and_b32 s101, s4, 1
	s_add_i32 s101, s101, 1
	s_lshr_b32 s5, s4, 1
	s_add_i32 s20, s5, 0x100
	s_sub_i32 s5, s10, 0x100
	s_lshl_b32 s5, s5, 1
	s_cmp_lt_u32 s4, s5
	s_cselect_b32 s20, s20, 0x7fff
.Ltail6_ns:
	v_mov_b64_e32 v[2:3], s[10:11]
	v_cmp_ge_i64_e32 vcc, s[20:21], v[2:3]
	v_cmp_lt_i64_e64 s[4:5], s[20:21], v[2:3]
	s_cbranch_vccnz .LBB0_780
	s_ashr_i32 s14, s20, 31
	s_lshr_b32 s14, s14, 29
	s_add_i32 s14, s20, s14
	s_ashr_i32 s15, s14, 3
	s_and_b32 s14, s14, -8
	s_sub_i32 s14, s20, s14
	s_lshr_b32 s16, s14, 31
	s_or_b32 s16, s3, s16
	s_mul_i32 s14, s16, s14
	s_add_i32 s14, s14, s15
	s_ashr_i32 s15, s14, 31
	s_lshr_b32 s15, s15, 27
	s_add_i32 s15, s14, s15
	s_ashr_i32 s16, s15, 5
	s_lshl_b32 s16, s16, 3
	v_readlane_b32 s17, v255, 35
	s_sub_i32 s17, s17, s16
	s_min_i32 s17, s17, 8
	s_abs_i32 s20, s17
	v_cvt_f32_u32_e32 v0, s20
	s_sub_i32 s22, 0, s20
	s_andn2_b32 s15, s15, 31
	s_sub_i32 s15, s14, s15
	v_rcp_iflag_f32_e32 v0, v0
	s_abs_i32 s14, s15
	s_xor_b32 s21, s15, s17
	s_ashr_i32 s21, s21, 31
	v_mul_f32_e32 v0, 0x4f7ffffe, v0
	v_cvt_u32_f32_e32 v0, v0
	s_nop 0
	v_readfirstlane_b32 s23, v0
	s_mul_i32 s22, s22, s23
	s_mul_hi_u32 s22, s23, s22
	s_add_i32 s23, s23, s22
	s_mul_hi_u32 s22, s14, s23
	s_mul_i32 s23, s22, s20
	s_sub_i32 s14, s14, s23
	s_add_i32 s39, s22, 1
	s_sub_i32 s23, s14, s20
	s_cmp_ge_u32 s14, s20
	s_cselect_b32 s22, s39, s22
	s_cselect_b32 s14, s23, s14
	s_add_i32 s23, s22, 1
	s_cmp_ge_u32 s14, s20
	s_cselect_b32 s14, s23, s22
	s_xor_b32 s14, s14, s21
	s_sub_i32 s14, s14, s21
	s_mul_i32 s17, s14, s17
	s_sub_i32 s15, s15, s17
	s_add_i32 s16, s15, s16

; #define PG8_STAGE(bufoff, gbase, voff) do { _Pragma("unroll") for (int _i = 0; _i < 2; ++_i) \
;         __builtin_amdgcn_global_load_lds((const unsigned*)((const char*)(gbase) + (voff)[_i]), (LAS unsigned*)(lds + (bufoff) + ldsw + _i * 8192), 16, 0, 0); } while (0)
; #define PG8_LDA(dst, b, h) do { _Pragma("unroll") for (int m = 0; m < 4; ++m) _Pragma("unroll") for (int k = 0; k < 2; ++k) dst[m][k] = *(const LAS bf16x8*)(lds + PG8_SA(b, h) + aoff + m * 2048 + k * 1024); } while (0)
; #define PG8_LDB(dst, b, h) do { _Pragma("unroll") for (int n = 0; n < 2; ++n) _Pragma("unroll") for (int k = 0; k < 2; ++k) dst[n][k] = *(const LAS bf16x8*)(lds + PG8_SB(b, h) + boff + n * 2048 + k * 1024); } while (0)
; #define PG8_MMA(ai, bj, At, Bt) do { __builtin_amdgcn_s_setprio(1); _Pragma("unroll") for (int m = 0; m < 4; ++m) _Pragma("unroll") for (int n = 0; n < 2; ++n) _Pragma("unroll") for (int k = 0; k < 2; ++k) \
;         acc[ai][bj][m][n] = __builtin_amdgcn_mfma_f32_16x16x32_bf16(Bt[n][k], At[m][k], acc[ai][bj][m][n], 0, 0, 0); __builtin_amdgcn_s_setprio(0); } while (0)
; #define PG8_WAIT_V(n) asm volatile("s_waitcnt vmcnt(" #n ")" ::: "memory")
; #define PG8_WAIT_L(n) asm volatile("s_waitcnt lgkmcnt(" #n ")" ::: "memory")
; #define PG8_BAR __builtin_amdgcn_s_barrier()
; #define PG8_SCHED __builtin_amdgcn_sched_barrier(0)
; template <class Epi, bool GS = false>
; __device__ __forceinline__ void gemm_phase(LAS unsigned char* lds, const Gemm g, const StaticOrder& S, const Epi& E, const int tid) {
;     ...
;         for (int t = tg; t < tg + seg; t += 2) {
;             const bool last = (t == nt - 2);
;             const char* a1 = cA + (size_t)(t + 1) * kstep;
;             const char* a2 = last ? nA : cA + (size_t)(t + 2) * kstep; const char* b2 = last ? nB : cB + (size_t)(t + 2) * kstep;
;             const char* a3 = a2 + kstep; const char* b3 = b2 + kstep;
;             PG8_LDB(B0, 0, 0); PG8_LDB(B1, 0, 1); PG8_SCHED; PG8_LDA(At, 0, 0); PG8_STAGE(PG8_SA(1, 1), a1 + hstepA, voffA);
;             PG8_WAIT_V(8); PG8_WAIT_L(0); PG8_BAR; PG8_MMA(0, 0, At, B0); PG8_MMA(0, 1, At, B1); PG8_BAR; PG8_SCHED;
;             PG8_LDA(At, 0, 1); PG8_STAGE(PG8_SB(0, 0), b2, voffB); PG8_STAGE(PG8_SB(0, 1), b2 + hstepB, voffB); PG8_STAGE(PG8_SA(0, 0), a2, voffA);
;             PG8_WAIT_V(8); PG8_WAIT_L(0); PG8_BAR; PG8_MMA(1, 0, At, B0); PG8_MMA(1, 1, At, B1); PG8_BAR; PG8_SCHED;
.LBB0_781:
	s_add_u32 s44, s42, 0xfffc0080
	s_addc_u32 s45, s43, -1
	s_add_i32 s58, 0, 0x10000
	s_cmp_eq_u32 s57, 12
	s_cselect_b32 s47, s17, s45
	s_cselect_b32 s46, s39, s44
	v_add_u32_e32 v0, s58, v190
	s_cselect_b32 s45, s15, s56
	s_cselect_b32 s44, s54, s55
	s_add_i32 s60, 0, 0x14000
	ds_read_b128 v[130:133], v0
	ds_read_b128 v[134:137], v0 offset:1024
	ds_read_b128 v[138:141], v0 offset:2048
	ds_read_b128 v[142:145], v0 offset:3072
	v_add_u32_e32 v0, s60, v190
	ds_read_b128 v[146:149], v0
	ds_read_b128 v[150:153], v0 offset:1024
	ds_read_b128 v[154:157], v0 offset:2048
	ds_read_b128 v[158:161], v0 offset:3072
	v_lshl_add_u64 v[170:171], s[42:43], 0, v[176:177]
	s_add_i32 m0, s37, 0xc000
	ds_read_b128 v[180:183], v192
	ds_read_b128 v[184:187], v192 offset:1024
	ds_read_b128 v[216:219], v192 offset:2048
	ds_read_b128 v[220:223], v192 offset:3072
	ds_read_b128 v[224:227], v192 offset:4096
	ds_read_b128 v[228:231], v192 offset:5120
	ds_read_b128 v[232:235], v192 offset:6144
	ds_read_b128 v[236:239], v192 offset:7168
	global_load_lds_dwordx4 v[170:171], off
	v_lshl_add_u64 v[170:171], s[42:43], 0, v[178:179]
	s_add_i32 m0, s37, 0xe000
	s_nop 0
	global_load_lds_dwordx4 v[170:171], off
	s_waitcnt vmcnt(8)
	s_waitcnt lgkmcnt(0)
	s_barrier
	s_setprio 1
	s_waitcnt lgkmcnt(0)
	s_cmp_eq_u32 s100, 2
	s_cbranch_scc1 .Ltail6_skip0
	v_mfma_f32_16x16x32_bf16 v[126:129], v[130:133], v[180:183], v[126:129]
	v_mfma_f32_16x16x32_bf16 v[122:125], v[138:141], v[180:183], v[122:125]
	v_mfma_f32_16x16x32_bf16 v[110:113], v[130:133], v[216:219], v[110:113]
	v_mfma_f32_16x16x32_bf16 v[106:109], v[138:141], v[216:219], v[106:109]
	v_mfma_f32_16x16x32_bf16 v[94:97], v[130:133], v[224:227], v[94:97]
	v_mfma_f32_16x16x32_bf16 v[90:93], v[138:141], v[224:227], v[90:93]
	v_mfma_f32_16x16x32_bf16 v[82:85], v[130:133], v[232:235], v[82:85]
	v_mfma_f32_16x16x32_bf16 v[78:81], v[138:141], v[232:235], v[78:81]
	v_mfma_f32_16x16x32_bf16 v[126:129], v[134:137], v[184:187], v[126:129]
	v_mfma_f32_16x16x32_bf16 v[122:125], v[142:145], v[184:187], v[122:125]
	v_mfma_f32_16x16x32_bf16 v[110:113], v[134:137], v[220:223], v[110:113]
	v_mfma_f32_16x16x32_bf16 v[106:109], v[142:145], v[220:223], v[106:109]
	v_mfma_f32_16x16x32_bf16 v[94:97], v[134:137], v[228:231], v[94:97]
	v_mfma_f32_16x16x32_bf16 v[90:93], v[142:145], v[228:231], v[90:93]
	v_mfma_f32_16x16x32_bf16 v[82:85], v[134:137], v[236:239], v[82:85]
	v_mfma_f32_16x16x32_bf16 v[78:81], v[142:145], v[236:239], v[78:81]
	s_setprio 0
	s_setprio 1
	v_mfma_f32_16x16x32_bf16 v[118:121], v[146:149], v[180:183], v[118:121]
	v_mfma_f32_16x16x32_bf16 v[114:117], v[154:157], v[180:183], v[114:117]
	v_mfma_f32_16x16x32_bf16 v[102:105], v[146:149], v[216:219], v[102:105]
	v_mfma_f32_16x16x32_bf16 v[98:101], v[154:157], v[216:219], v[98:101]
	v_mfma_f32_16x16x32_bf16 v[86:89], v[146:149], v[224:227], v[86:89]
	v_mfma_f32_16x16x32_bf16 v[74:77], v[154:157], v[224:227], v[74:77]
	v_mfma_f32_16x16x32_bf16 v[70:73], v[146:149], v[232:235], v[70:73]
	v_mfma_f32_16x16x32_bf16 v[66:69], v[154:157], v[232:235], v[66:69]
	v_mfma_f32_16x16x32_bf16 v[118:121], v[150:153], v[184:187], v[118:121]
	v_mfma_f32_16x16x32_bf16 v[114:117], v[158:161], v[184:187], v[114:117]
	v_mfma_f32_16x16x32_bf16 v[102:105], v[150:153], v[220:223], v[102:105]
	v_mfma_f32_16x16x32_bf16 v[98:101], v[158:161], v[220:223], v[98:101]
	v_mfma_f32_16x16x32_bf16 v[86:89], v[150:153], v[228:231], v[86:89]
	v_mfma_f32_16x16x32_bf16 v[74:77], v[158:161], v[228:231], v[74:77]
	v_mfma_f32_16x16x32_bf16 v[70:73], v[150:153], v[236:239], v[70:73]
	v_mfma_f32_16x16x32_bf16 v[66:69], v[158:161], v[236:239], v[66:69]
	s_setprio 0
.Ltail6_skip0:
	s_setprio 0
	s_barrier
	s_add_i32 s58, s58, s2
	v_lshl_add_u64 v[170:171], s[44:45], 0, v[164:165]
	s_mov_b32 m0, s58
	ds_read_b128 v[180:183], v192 offset:16384
	ds_read_b128 v[184:187], v192 offset:17408
	ds_read_b128 v[216:219], v192 offset:18432
	ds_read_b128 v[220:223], v192 offset:19456
	ds_read_b128 v[224:227], v192 offset:20480
	ds_read_b128 v[228:231], v192 offset:21504
	ds_read_b128 v[232:235], v192 offset:22528
	ds_read_b128 v[236:239], v192 offset:23552
	global_load_lds_dwordx4 v[170:171], off
	s_add_i32 m0, s58, 0x2000
	s_add_u32 s58, s44, 0x40000
	v_lshl_add_u64 v[172:173], s[44:45], 0, v[162:163]
	s_addc_u32 s59, s45, 0
	s_add_i32 s60, s60, s2
	global_load_lds_dwordx4 v[172:173], off
	v_lshl_add_u64 v[188:189], s[58:59], 0, v[164:165]
	s_mov_b32 m0, s60
	v_lshl_add_u64 v[194:195], s[46:47], 0, v[162:163]
	global_load_lds_dwordx4 v[188:189], off
	v_lshl_add_u64 v[188:189], s[58:59], 0, v[162:163]
	s_add_i32 m0, s60, 0x2000
	s_nop 0
	global_load_lds_dwordx4 v[188:189], off
	v_lshl_add_u64 v[188:189], s[46:47], 0, v[164:165]
	s_mov_b32 m0, s37
	s_nop 0
	global_load_lds_dwordx4 v[188:189], off
	s_mov_b32 m0, s41
	s_nop 0
	global_load_lds_dwordx4 v[194:195], off
	s_waitcnt vmcnt(8)
	s_waitcnt lgkmcnt(0)
	s_barrier
	s_setprio 1
	s_waitcnt lgkmcnt(0)
	s_cmp_eq_u32 s100, 1
	s_cbranch_scc1 .Ltail6_skip1
; #define PG8_STAGE(bufoff, gbase, voff) do { _Pragma("unroll") for (int _i = 0; _i < 2; ++_i) \
;         __builtin_amdgcn_global_load_lds((const unsigned*)((const char*)(gbase) + (voff)[_i]), (LAS unsigned*)(lds + (bufoff) + ldsw + _i * 8192), 16, 0, 0); } while (0)
; #define PG8_LDA(dst, b, h) do { _Pragma("unroll") for (int m = 0; m < 4; ++m) _Pragma("unroll") for (int k = 0; k < 2; ++k) dst[m][k] = *(const LAS bf16x8*)(lds + PG8_SA(b, h) + aoff + m * 2048 + k * 1024); } while (0)
; #define PG8_LDB(dst, b, h) do { _Pragma("unroll") for (int n = 0; n < 2; ++n) _Pragma("unroll") for (int k = 0; k < 2; ++k) dst[n][k] = *(const LAS bf16x8*)(lds + PG8_SB(b, h) + boff + n * 2048 + k * 1024); } while (0)
; #define PG8_MMA(ai, bj, At, Bt) do { __builtin_amdgcn_s_setprio(1); _Pragma("unroll") for (int m = 0; m < 4; ++m) _Pragma("unroll") for (int n = 0; n < 2; ++n) _Pragma("unroll") for (int k = 0; k < 2; ++k) \
;         acc[ai][bj][m][n] = __builtin_amdgcn_mfma_f32_16x16x32_bf16(Bt[n][k], At[m][k], acc[ai][bj][m][n], 0, 0, 0); __builtin_amdgcn_s_setprio(0); } while (0)
; #define PG8_WAIT_V(n) asm volatile("s_waitcnt vmcnt(" #n ")" ::: "memory")
; #define PG8_WAIT_L(n) asm volatile("s_waitcnt lgkmcnt(" #n ")" ::: "memory")
; #define PG8_BAR __builtin_amdgcn_s_barrier()
; #define PG8_SCHED __builtin_amdgcn_sched_barrier(0)
; template <class Epi, bool GS = false>
; __device__ __forceinline__ void gemm_phase(LAS unsigned char* lds, const Gemm g, const StaticOrder& S, const Epi& E, const int tid) {
;     ...
;             PG8_WAIT_V(8); PG8_WAIT_L(0); PG8_BAR; PG8_MMA(0, 0, At, B0); PG8_MMA(0, 1, At, B1); PG8_BAR; PG8_SCHED;
;             PG8_LDA(At, 0, 1); PG8_STAGE(PG8_SB(0, 0), b2, voffB); PG8_STAGE(PG8_SB(0, 1), b2 + hstepB, voffB); PG8_STAGE(PG8_SA(0, 0), a2, voffA);
;             PG8_WAIT_V(8); PG8_WAIT_L(0); PG8_BAR; PG8_MMA(1, 0, At, B0); PG8_MMA(1, 1, At, B1); PG8_BAR; PG8_SCHED;
;             PG8_LDB(B0, 1, 0); PG8_LDB(B1, 1, 1); PG8_SCHED; PG8_LDA(At, 1, 0); PG8_STAGE(PG8_SA(0, 1), a2 + hstepA, voffA);
;             PG8_WAIT_V(8); PG8_WAIT_L(0); PG8_BAR; PG8_MMA(0, 0, At, B0); PG8_MMA(0, 1, At, B1); PG8_BAR; PG8_SCHED;
	v_mfma_f32_16x16x32_bf16 v[62:65], v[130:133], v[180:183], v[62:65]
	v_mfma_f32_16x16x32_bf16 v[58:61], v[138:141], v[180:183], v[58:61]
	v_mfma_f32_16x16x32_bf16 v[46:49], v[130:133], v[216:219], v[46:49]
	v_mfma_f32_16x16x32_bf16 v[42:45], v[138:141], v[216:219], v[42:45]
	v_mfma_f32_16x16x32_bf16 v[30:33], v[130:133], v[224:227], v[30:33]
	v_mfma_f32_16x16x32_bf16 v[26:29], v[138:141], v[224:227], v[26:29]
	v_mfma_f32_16x16x32_bf16 v[14:17], v[130:133], v[232:235], v[14:17]
	v_mfma_f32_16x16x32_bf16 v[10:13], v[138:141], v[232:235], v[10:13]
	v_mfma_f32_16x16x32_bf16 v[62:65], v[134:137], v[184:187], v[62:65]
	v_mfma_f32_16x16x32_bf16 v[58:61], v[142:145], v[184:187], v[58:61]
	v_mfma_f32_16x16x32_bf16 v[46:49], v[134:137], v[220:223], v[46:49]
	v_mfma_f32_16x16x32_bf16 v[42:45], v[142:145], v[220:223], v[42:45]
	v_mfma_f32_16x16x32_bf16 v[30:33], v[134:137], v[228:231], v[30:33]
	v_mfma_f32_16x16x32_bf16 v[26:29], v[142:145], v[228:231], v[26:29]
	v_mfma_f32_16x16x32_bf16 v[14:17], v[134:137], v[236:239], v[14:17]
	v_mfma_f32_16x16x32_bf16 v[10:13], v[142:145], v[236:239], v[10:13]
	s_setprio 0
	s_setprio 1
	v_mfma_f32_16x16x32_bf16 v[54:57], v[146:149], v[180:183], v[54:57]
	v_mfma_f32_16x16x32_bf16 v[50:53], v[154:157], v[180:183], v[50:53]
	v_mfma_f32_16x16x32_bf16 v[38:41], v[146:149], v[216:219], v[38:41]
	v_mfma_f32_16x16x32_bf16 v[34:37], v[154:157], v[216:219], v[34:37]
	v_mfma_f32_16x16x32_bf16 v[22:25], v[146:149], v[224:227], v[22:25]
	v_mfma_f32_16x16x32_bf16 v[18:21], v[154:157], v[224:227], v[18:21]
	v_mfma_f32_16x16x32_bf16 v[6:9], v[146:149], v[232:235], v[6:9]
	v_mfma_f32_16x16x32_bf16 v[2:5], v[154:157], v[232:235], v[2:5]
	v_mfma_f32_16x16x32_bf16 v[54:57], v[150:153], v[184:187], v[54:57]
	v_mfma_f32_16x16x32_bf16 v[50:53], v[158:161], v[184:187], v[50:53]
	v_mfma_f32_16x16x32_bf16 v[38:41], v[150:153], v[220:223], v[38:41]
	v_mfma_f32_16x16x32_bf16 v[34:37], v[158:161], v[220:223], v[34:37]
	v_mfma_f32_16x16x32_bf16 v[22:25], v[150:153], v[228:231], v[22:25]
	v_mfma_f32_16x16x32_bf16 v[18:21], v[158:161], v[228:231], v[18:21]
	v_mfma_f32_16x16x32_bf16 v[6:9], v[150:153], v[236:239], v[6:9]
	v_mfma_f32_16x16x32_bf16 v[2:5], v[158:161], v[236:239], v[2:5]
	s_setprio 0
.Ltail6_skip1:
	s_setprio 0
	s_barrier
	s_add_i32 s58, 0, 0x18000
	v_add_u32_e32 v0, s58, v190
	s_add_i32 s59, 0, 0x1c000
	ds_read_b128 v[130:133], v0
	ds_read_b128 v[134:137], v0 offset:1024
	ds_read_b128 v[138:141], v0 offset:2048
	ds_read_b128 v[142:145], v0 offset:3072
	v_add_u32_e32 v0, s59, v190
	ds_read_b128 v[146:149], v0
	ds_read_b128 v[150:153], v0 offset:1024
	ds_read_b128 v[154:157], v0 offset:2048
	ds_read_b128 v[158:161], v0 offset:3072
	s_add_u32 s46, s46, 0x40000
	s_addc_u32 s47, s47, 0
	s_mov_b32 m0, s48
	v_lshl_add_u64 v[240:241], s[46:47], 0, v[164:165]
	ds_read_b128 v[180:183], v192 offset:32768
	ds_read_b128 v[184:187], v192 offset:33792
	ds_read_b128 v[216:219], v192 offset:34816
	ds_read_b128 v[220:223], v192 offset:35840
	ds_read_b128 v[224:227], v192 offset:36864
	ds_read_b128 v[228:231], v192 offset:37888
	ds_read_b128 v[232:235], v192 offset:38912
	ds_read_b128 v[236:239], v192 offset:39936
	global_load_lds_dwordx4 v[240:241], off
	v_lshl_add_u64 v[240:241], s[46:47], 0, v[162:163]
	s_mov_b32 m0, s49
	s_nop 0
	global_load_lds_dwordx4 v[240:241], off
	s_waitcnt vmcnt(8)
	s_waitcnt lgkmcnt(0)
	s_barrier
	s_setprio 1
	s_waitcnt lgkmcnt(0)
	s_cmp_eq_u32 s100, 2
	s_cbranch_scc1 .Ltail6_skip2
	v_mfma_f32_16x16x32_bf16 v[126:129], v[130:133], v[180:183], v[126:129]
	v_mfma_f32_16x16x32_bf16 v[122:125], v[138:141], v[180:183], v[122:125]
	v_mfma_f32_16x16x32_bf16 v[110:113], v[130:133], v[216:219], v[110:113]
	v_mfma_f32_16x16x32_bf16 v[106:109], v[138:141], v[216:219], v[106:109]
	v_mfma_f32_16x16x32_bf16 v[94:97], v[130:133], v[224:227], v[94:97]
	v_mfma_f32_16x16x32_bf16 v[90:93], v[138:141], v[224:227], v[90:93]
	v_mfma_f32_16x16x32_bf16 v[82:85], v[130:133], v[232:235], v[82:85]
	v_mfma_f32_16x16x32_bf16 v[78:81], v[138:141], v[232:235], v[78:81]
	v_mfma_f32_16x16x32_bf16 v[126:129], v[134:137], v[184:187], v[126:129]
	v_mfma_f32_16x16x32_bf16 v[122:125], v[142:145], v[184:187], v[122:125]
	v_mfma_f32_16x16x32_bf16 v[110:113], v[134:137], v[220:223], v[110:113]
	v_mfma_f32_16x16x32_bf16 v[106:109], v[142:145], v[220:223], v[106:109]
	v_mfma_f32_16x16x32_bf16 v[94:97], v[134:137], v[228:231], v[94:97]
	v_mfma_f32_16x16x32_bf16 v[90:93], v[142:145], v[228:231], v[90:93]
	v_mfma_f32_16x16x32_bf16 v[82:85], v[134:137], v[236:239], v[82:85]
	v_mfma_f32_16x16x32_bf16 v[78:81], v[142:145], v[236:239], v[78:81]
	s_setprio 0
	s_setprio 1
	v_mfma_f32_16x16x32_bf16 v[118:121], v[146:149], v[180:183], v[118:121]
	v_mfma_f32_16x16x32_bf16 v[114:117], v[154:157], v[180:183], v[114:117]
	v_mfma_f32_16x16x32_bf16 v[102:105], v[146:149], v[216:219], v[102:105]
	v_mfma_f32_16x16x32_bf16 v[98:101], v[154:157], v[216:219], v[98:101]
	v_mfma_f32_16x16x32_bf16 v[86:89], v[146:149], v[224:227], v[86:89]
	v_mfma_f32_16x16x32_bf16 v[74:77], v[154:157], v[224:227], v[74:77]
	v_mfma_f32_16x16x32_bf16 v[70:73], v[146:149], v[232:235], v[70:73]
	v_mfma_f32_16x16x32_bf16 v[66:69], v[154:157], v[232:235], v[66:69]
	v_mfma_f32_16x16x32_bf16 v[118:121], v[150:153], v[184:187], v[118:121]
	v_mfma_f32_16x16x32_bf16 v[114:117], v[158:161], v[184:187], v[114:117]
	v_mfma_f32_16x16x32_bf16 v[102:105], v[150:153], v[220:223], v[102:105]
	v_mfma_f32_16x16x32_bf16 v[98:101], v[158:161], v[220:223], v[98:101]
	v_mfma_f32_16x16x32_bf16 v[86:89], v[150:153], v[228:231], v[86:89]
	v_mfma_f32_16x16x32_bf16 v[74:77], v[158:161], v[228:231], v[74:77]
	v_mfma_f32_16x16x32_bf16 v[70:73], v[150:153], v[236:239], v[70:73]
	v_mfma_f32_16x16x32_bf16 v[66:69], v[158:161], v[236:239], v[66:69]
	s_setprio 0
; #define PG8_STAGE(bufoff, gbase, voff) do { _Pragma("unroll") for (int _i = 0; _i < 2; ++_i) \
;         __builtin_amdgcn_global_load_lds((const unsigned*)((const char*)(gbase) + (voff)[_i]), (LAS unsigned*)(lds + (bufoff) + ldsw + _i * 8192), 16, 0, 0); } while (0)
; #define PG8_LDA(dst, b, h) do { _Pragma("unroll") for (int m = 0; m < 4; ++m) _Pragma("unroll") for (int k = 0; k < 2; ++k) dst[m][k] = *(const LAS bf16x8*)(lds + PG8_SA(b, h) + aoff + m * 2048 + k * 1024); } while (0)
; #define PG8_WAIT_V(n) asm volatile("s_waitcnt vmcnt(" #n ")" ::: "memory")
; template <class Epi, bool GS = false>
; __device__ __forceinline__ void gemm_phase(LAS unsigned char* lds, const Gemm g, const StaticOrder& S, const Epi& E, const int tid) {
;     ...
;             PG8_WAIT_V(8); PG8_WAIT_L(0); PG8_BAR; PG8_MMA(0, 0, At, B0); PG8_MMA(0, 1, At, B1); PG8_BAR; PG8_SCHED;
;             PG8_LDA(At, 1, 1); PG8_STAGE(PG8_SB(1, 0), b3, voffB); PG8_STAGE(PG8_SB(1, 1), b3 + hstepB, voffB); PG8_STAGE(PG8_SA(1, 0), a3, voffA);
;             PG8_WAIT_V(8); PG8_WAIT_L(0); PG8_BAR; PG8_MMA(1, 0, At, B0); PG8_MMA(1, 1, At, B1); PG8_BAR; PG8_SCHED;
;         }
;     __device__ __forceinline__ void operator()(const f32x4 (&acc)[2][2][4][2], const Unit& u, int wr, int wc, int fr, int fq) const {
;         const int col0 = u.pn * BM + wc * 32 + 4 * fq;
; #pragma unroll
;         for (int ai = 0; ai < 2; ++ai) {
;             const int grb = row_base + u.pm * BM + ai * HALF + wr * 64;
;             const int seq = grb < MP ? (grb >> 11) : NPB + ((grb - MP) >> 6);
;             const float* gp = gate + (size_t)seq * (6 * DM) + col0;
;             f32x4 gv[2][2];
; #pragma unroll
;             for (int bj = 0; bj < 2; ++bj)
; #pragma unroll
;                 for (int n = 0; n < 2; ++n) gv[bj][n] = *(const f32x4*)(gp + bj * HALF + n * 16);
;             if (u.part == 0) {
; #pragma unroll
;                 for (int mp = 0; mp < 2; ++mp) {
;                 f32x4 xv[2][2][2];
; #pragma unroll
;                 for (int mm = 0; mm < 2; ++mm) { const int gr = grb + (2 * mp + mm) * 16 + fr;
;                     const float* xr = (gr < MP ? xin_p + (size_t)gr * DM : xin_s + (size_t)(gr - MP) * DM) + col0;
; #pragma unroll
;                     for (int bj = 0; bj < 2; ++bj)
; #pragma unroll
;                         for (int n = 0; n < 2; ++n) xv[mm][bj][n] = *(const f32x4*)(xr + bj * HALF + n * 16); }
.Ltail6_skip2:
	s_setprio 0
	s_barrier
	s_add_i32 s46, s58, s2
	v_lshl_add_u64 v[170:171], v[170:171], 0, s[0:1]
	s_mov_b32 m0, s46
	ds_read_b128 v[180:183], v192 offset:49152
	ds_read_b128 v[184:187], v192 offset:50176
	ds_read_b128 v[216:219], v192 offset:51200
	ds_read_b128 v[220:223], v192 offset:52224
	ds_read_b128 v[224:227], v192 offset:53248
	ds_read_b128 v[228:231], v192 offset:54272
	ds_read_b128 v[232:235], v192 offset:55296
	ds_read_b128 v[236:239], v192 offset:56320
	global_load_lds_dwordx4 v[170:171], off
	s_add_i32 m0, s46, 0x2000
	s_add_u32 s44, s44, 0x40080
	v_lshl_add_u64 v[170:171], v[172:173], 0, s[0:1]
	s_addc_u32 s45, s45, 0
	s_add_i32 s46, s59, s2
	global_load_lds_dwordx4 v[170:171], off
	v_lshl_add_u64 v[170:171], s[44:45], 0, v[164:165]
	s_mov_b32 m0, s46
	s_nop 0
	global_load_lds_dwordx4 v[170:171], off
	v_lshl_add_u64 v[170:171], s[44:45], 0, v[162:163]
	s_add_i32 m0, s46, 0x2000
	s_nop 0
	global_load_lds_dwordx4 v[170:171], off
	v_lshl_add_u64 v[170:171], v[188:189], 0, s[0:1]
	s_mov_b32 m0, s50
	s_nop 0
	global_load_lds_dwordx4 v[170:171], off
	v_lshl_add_u64 v[170:171], v[194:195], 0, s[0:1]
	s_mov_b32 m0, s51
	s_nop 0
	global_load_lds_dwordx4 v[170:171], off
	s_waitcnt vmcnt(8)
	s_waitcnt lgkmcnt(0)
	s_barrier
	s_setprio 1
	s_waitcnt lgkmcnt(0)
	s_cmp_eq_u32 s100, 1
	s_cbranch_scc1 .Ltail6_skip3
	v_mfma_f32_16x16x32_bf16 v[62:65], v[130:133], v[180:183], v[62:65]
	v_mfma_f32_16x16x32_bf16 v[58:61], v[138:141], v[180:183], v[58:61]
	v_mfma_f32_16x16x32_bf16 v[46:49], v[130:133], v[216:219], v[46:49]
	v_mfma_f32_16x16x32_bf16 v[42:45], v[138:141], v[216:219], v[42:45]
	v_mfma_f32_16x16x32_bf16 v[30:33], v[130:133], v[224:227], v[30:33]
	v_mfma_f32_16x16x32_bf16 v[26:29], v[138:141], v[224:227], v[26:29]
	v_mfma_f32_16x16x32_bf16 v[14:17], v[130:133], v[232:235], v[14:17]
	v_mfma_f32_16x16x32_bf16 v[10:13], v[138:141], v[232:235], v[10:13]
	v_mfma_f32_16x16x32_bf16 v[62:65], v[134:137], v[184:187], v[62:65]
	v_mfma_f32_16x16x32_bf16 v[58:61], v[142:145], v[184:187], v[58:61]
	v_mfma_f32_16x16x32_bf16 v[46:49], v[134:137], v[220:223], v[46:49]
	v_mfma_f32_16x16x32_bf16 v[42:45], v[142:145], v[220:223], v[42:45]
	v_mfma_f32_16x16x32_bf16 v[30:33], v[134:137], v[228:231], v[30:33]
	v_mfma_f32_16x16x32_bf16 v[26:29], v[142:145], v[228:231], v[26:29]
	v_mfma_f32_16x16x32_bf16 v[14:17], v[134:137], v[236:239], v[14:17]
	v_mfma_f32_16x16x32_bf16 v[10:13], v[142:145], v[236:239], v[10:13]
	s_setprio 0
	s_setprio 1
	v_mfma_f32_16x16x32_bf16 v[54:57], v[146:149], v[180:183], v[54:57]
	v_mfma_f32_16x16x32_bf16 v[50:53], v[154:157], v[180:183], v[50:53]
	v_mfma_f32_16x16x32_bf16 v[38:41], v[146:149], v[216:219], v[38:41]
	v_mfma_f32_16x16x32_bf16 v[34:37], v[154:157], v[216:219], v[34:37]
	v_mfma_f32_16x16x32_bf16 v[22:25], v[146:149], v[224:227], v[22:25]
	v_mfma_f32_16x16x32_bf16 v[18:21], v[154:157], v[224:227], v[18:21]
	v_mfma_f32_16x16x32_bf16 v[6:9], v[146:149], v[232:235], v[6:9]
	v_mfma_f32_16x16x32_bf16 v[2:5], v[154:157], v[232:235], v[2:5]
	v_mfma_f32_16x16x32_bf16 v[54:57], v[150:153], v[184:187], v[54:57]
	v_mfma_f32_16x16x32_bf16 v[50:53], v[158:161], v[184:187], v[50:53]
	v_mfma_f32_16x16x32_bf16 v[38:41], v[150:153], v[220:223], v[38:41]
	v_mfma_f32_16x16x32_bf16 v[34:37], v[158:161], v[220:223], v[34:37]
	v_mfma_f32_16x16x32_bf16 v[22:25], v[150:153], v[228:231], v[22:25]
	v_mfma_f32_16x16x32_bf16 v[18:21], v[158:161], v[228:231], v[18:21]
	v_mfma_f32_16x16x32_bf16 v[6:9], v[150:153], v[236:239], v[6:9]
	v_mfma_f32_16x16x32_bf16 v[2:5], v[158:161], v[236:239], v[2:5]
	s_setprio 0
.Ltail6_skip3:
	s_setprio 0
	s_barrier
	s_add_i32 s57, s57, 2
	s_add_u32 s42, s42, 0x100
	s_addc_u32 s43, s43, 0
	s_add_u32 s55, s55, 0x100
	s_addc_u32 s56, s56, 0
	s_cmp_gt_u32 s57, 13
	s_cbranch_scc0 .LBB0_781
	s_and_b64 vcc, exec, s[8:9]
	s_cbranch_vccz .LBB0_784
	s_barrier
.LBB0_784:
	s_lshl_b32 s15, s38, 8
	s_add_i32 s17, s36, s15
	s_add_i32 s39, s17, 0xffff8000
	s_lshr_b32 s39, s39, 6
	s_ashr_i32 s38, s17, 11
	s_add_i32 s39, s39, 16
	s_cmp_lt_i32 s17, 0x8000
	v_or_b32_e32 v182, s17, v169
	s_mov_b32 s17, 0x8000
	v_add_u32_e32 v0, 0xffff8000, v182
	v_cmp_gt_i32_e32 vcc, s17, v182
	s_cselect_b32 s38, s38, s39
	v_ashrrev_i32_e32 v183, 31, v182
	v_cndmask_b32_e32 v146, v0, v182, vcc
	v_mov_b32_e32 v0, s35
	v_mov_b32_e32 v148, s31
	v_lshl_or_b32 v130, s40, 8, v191
	s_mul_hi_i32 s39, s38, 0x6000
	s_mulk_i32 s38, 0x6000
	v_readlane_b32 s28, v255, 25
	v_cndmask_b32_e32 v147, 0, v183, vcc
	v_cndmask_b32_e32 v149, v0, v148, vcc
	v_mov_b32_e32 v0, s34
	v_mov_b32_e32 v148, s30
	v_ashrrev_i32_e32 v131, 31, v130
	s_add_u32 s38, s28, s38
	v_readlane_b32 s28, v255, 27
	v_cndmask_b32_e32 v148, v0, v148, vcc
	v_lshlrev_b64 v[146:147], 12, v[146:147]
	s_addc_u32 s39, s28, s39
	v_lshlrev_b64 v[180:181], 2, v[130:131]
	v_lshl_add_u64 v[146:147], v[148:149], 0, v[146:147]
	v_lshl_add_u64 v[130:131], s[38:39], 0, v[180:181]
	v_lshl_add_u64 v[146:147], v[146:147], 0, v[180:181]
	global_load_dwordx4 v[142:145], v[130:131], off
	global_load_dwordx4 v[138:141], v[130:131], off offset:64
	global_load_dwordx4 v[134:137], v[130:131], off offset:512
	s_nop 0
	global_load_dwordx4 v[130:133], v[130:131], off offset:576
	s_nop 0
	global_load_dwordx4 v[158:161], v[146:147], off
	global_load_dwordx4 v[154:157], v[146:147], off offset:64
	global_load_dwordx4 v[150:153], v[146:147], off offset:512
	s_nop 0
	global_load_dwordx4 v[146:149], v[146:147], off offset:576
	v_or_b32_e32 v186, 16, v182
	s_movk_i32 s17, 0x7fff
	v_cmp_lt_i32_e32 vcc, s17, v186
	s_and_saveexec_b64 s[38:39], vcc
	s_xor_b64 s[38:39], exec, s[38:39]
	v_add_u32_e32 v0, 0xffff8010, v182
	v_lshlrev_b64 v[170:171], 12, v[0:1]
	v_mov_b32_e32 v187, v1
	v_lshl_add_u64 v[188:189], s[34:35], 0, v[170:171]
	v_lshlrev_b64 v[184:185], 12, v[186:187]
	s_andn2_saveexec_b64 s[38:39], s[38:39]
	v_ashrrev_i32_e32 v187, 31, v186
	v_lshlrev_b64 v[184:185], 12, v[186:187]
	v_lshl_add_u64 v[188:189], s[30:31], 0, v[184:185]
	s_or_b64 exec, exec, s[38:39]
	v_lshl_add_u64 v[170:171], v[188:189], 0, v[180:181]
	global_load_dwordx4 v[186:189], v[170:171], off
	global_load_dwordx4 v[216:219], v[170:171], off offset:64
	global_load_dwordx4 v[220:223], v[170:171], off offset:512
	global_load_dwordx4 v[224:227], v[170:171], off offset:576
	v_lshlrev_b64 v[170:171], 12, v[182:183]
	s_waitcnt vmcnt(0)
;     __device__ __forceinline__ void operator()(const f32x4 (&acc)[2][2][4][2], const Unit& u, int wr, int wc, int fr, int fq) const {
;     ...
;             if (u.part == 0) {
; #pragma unroll
;                 for (int mp = 0; mp < 2; ++mp) {
;                 f32x4 xv[2][2][2];
; #pragma unroll
;                 for (int mm = 0; mm < 2; ++mm) { const int gr = grb + (2 * mp + mm) * 16 + fr;
;                     const float* xr = (gr < MP ? xin_p + (size_t)gr * DM : xin_s + (size_t)(gr - MP) * DM) + col0;
; #pragma unroll
;                     for (int bj = 0; bj < 2; ++bj)
; #pragma unroll
;                         for (int n = 0; n < 2; ++n) xv[mm][bj][n] = *(const f32x4*)(xr + bj * HALF + n * 16); }
; #pragma unroll
;                 for (int mm = 0; mm < 2; ++mm) { const int m = 2 * mp + mm; const int gr = grb + m * 16 + fr; float* orow = out + (size_t)gr * DM + col0;
; #pragma unroll
;                     for (int bj = 0; bj < 2; ++bj)
; #pragma unroll
;                         for (int n = 0; n < 2; ++n) *(f32x4*)(orow + bj * HALF + n * 16) = xv[mm][bj][n] + gv[bj][n] * acc[ai][bj][m][n]; }
;                 }
	v_pk_fma_f32 v[148:149], v[116:117], v[132:133], v[148:149]
	v_or_b32_e32 v116, 32, v182
	s_mov_b32 s17, 0x8000
	v_pk_fma_f32 v[118:119], v[118:119], v[134:135], v[150:151]
	v_add_u32_e32 v0, 0xffff8020, v182
	v_lshl_add_u64 v[150:151], s[24:25], 0, v[170:171]
	v_ashrrev_i32_e32 v117, 31, v116
	v_cmp_gt_i32_e32 vcc, s17, v116
	v_pk_fma_f32 v[128:129], v[128:129], v[144:145], v[160:161]
	v_pk_fma_f32 v[126:127], v[126:127], v[142:143], v[158:159]
	v_pk_fma_f32 v[124:125], v[124:125], v[140:141], v[156:157]
	v_pk_fma_f32 v[122:123], v[122:123], v[138:139], v[154:155]
	v_pk_fma_f32 v[120:121], v[120:121], v[136:137], v[152:153]
	v_mov_b32_e32 v154, s35
	v_mov_b32_e32 v155, s31
	v_mov_b32_e32 v156, s34
	v_mov_b32_e32 v157, s30
	v_lshl_add_u64 v[150:151], v[150:151], 0, v[180:181]
	v_cndmask_b32_e32 v153, 0, v117, vcc
	v_cndmask_b32_e32 v152, v0, v116, vcc
	v_pk_fma_f32 v[146:147], v[114:115], v[130:131], v[146:147]
	v_lshl_add_u64 v[114:115], s[24:25], 0, v[184:185]
	v_cndmask_b32_e32 v155, v154, v155, vcc
	v_cndmask_b32_e32 v154, v156, v157, vcc
	s_cmp_eq_u32 s100, 2
	s_cselect_b32 m0, 0, -1
	s_cselect_b64 exec, 0, -1
	global_store_dwordx4 v[150:151], v[126:129], off
	global_store_dwordx4 v[150:151], v[122:125], off offset:64
	global_store_dwordx4 v[150:151], v[118:121], off offset:512
	global_store_dwordx4 v[150:151], v[146:149], off offset:576
	s_mov_b64 exec, -1
	v_lshl_add_u64 v[114:115], v[114:115], 0, v[180:181]
	v_lshlrev_b64 v[118:119], 12, v[152:153]
	v_lshl_add_u64 v[118:119], v[154:155], 0, v[118:119]
	v_lshl_add_u64 v[118:119], v[118:119], 0, v[180:181]
	s_movk_i32 s17, 0x7fff
	v_pk_fma_f32 v[112:113], v[112:113], v[144:145], v[188:189]
	v_pk_fma_f32 v[110:111], v[110:111], v[142:143], v[186:187]
	v_pk_fma_f32 v[108:109], v[108:109], v[140:141], v[218:219]
	v_pk_fma_f32 v[106:107], v[106:107], v[138:139], v[216:217]
	v_pk_fma_f32 v[104:105], v[104:105], v[136:137], v[222:223]
	v_pk_fma_f32 v[102:103], v[102:103], v[134:135], v[220:221]
	v_pk_fma_f32 v[100:101], v[100:101], v[132:133], v[226:227]
	v_pk_fma_f32 v[98:99], v[98:99], v[130:131], v[224:225]
	s_cmp_eq_u32 s100, 2
	s_cselect_b64 exec, 0, -1
	global_store_dwordx4 v[114:115], v[110:113], off
	global_store_dwordx4 v[114:115], v[106:109], off offset:64
	global_store_dwordx4 v[114:115], v[102:105], off offset:512
	global_store_dwordx4 v[114:115], v[98:101], off offset:576
	s_mov_b64 exec, -1
	global_load_dwordx4 v[110:113], v[118:119], off
	s_nop 0
	global_load_dwordx4 v[106:109], v[118:119], off offset:64
	global_load_dwordx4 v[102:105], v[118:119], off offset:512
	global_load_dwordx4 v[98:101], v[118:119], off offset:576
	v_or_b32_e32 v118, 48, v182
	v_cmp_lt_i32_e32 vcc, s17, v118
	s_and_saveexec_b64 s[38:39], vcc
	s_xor_b64 s[38:39], exec, s[38:39]
	v_add_u32_e32 v0, 0xffff8030, v182
	v_lshlrev_b64 v[114:115], 12, v[0:1]
	v_mov_b32_e32 v119, v1
	v_lshl_add_u64 v[120:121], s[34:35], 0, v[114:115]
	v_lshlrev_b64 v[114:115], 12, v[118:119]
	s_andn2_saveexec_b64 s[38:39], s[38:39]
	v_ashrrev_i32_e32 v119, 31, v118
	v_lshlrev_b64 v[114:115], 12, v[118:119]
	v_lshl_add_u64 v[120:121], s[30:31], 0, v[114:115]
	s_or_b64 exec, exec, s[38:39]
	v_lshl_add_u64 v[146:147], v[120:121], 0, v[180:181]
	global_load_dwordx4 v[118:121], v[146:147], off
	global_load_dwordx4 v[122:125], v[146:147], off offset:64
	global_load_dwordx4 v[126:129], v[146:147], off offset:512
	s_nop 0
	global_load_dwordx4 v[146:149], v[146:147], off offset:576
	s_add_i32 s15, s52, s15
	s_add_i32 s38, s15, 0xffff8000
	v_lshlrev_b64 v[116:117], 12, v[116:117]
	s_lshr_b32 s38, s38, 6
	v_lshl_add_u64 v[116:117], s[24:25], 0, v[116:117]
	s_ashr_i32 s17, s15, 11
	s_add_i32 s38, s38, 16
	v_lshl_add_u64 v[116:117], v[116:117], 0, v[180:181]
	s_waitcnt vmcnt(4)
	v_pk_fma_f32 v[76:77], v[76:77], v[132:133], v[100:101]
	v_pk_fma_f32 v[74:75], v[74:75], v[130:131], v[98:99]
	s_cmp_lt_i32 s15, 0x8000
	v_or_b32_e32 v98, s15, v169
	s_mov_b32 s15, 0x8000
	v_pk_fma_f32 v[88:89], v[88:89], v[136:137], v[104:105]
	v_pk_fma_f32 v[86:87], v[86:87], v[134:135], v[102:103]
	s_mov_b32 exec_lo, m0
	s_mov_b32 exec_hi, m0
	global_store_dwordx4 v[116:117], v[74:77], off offset:576
	s_mov_b64 exec, -1
	v_cmp_gt_i32_e32 vcc, s15, v98
	v_add_u32_e32 v0, 0xffff8000, v98
	v_lshl_add_u64 v[74:75], s[24:25], 0, v[114:115]
	s_mov_b32 exec_lo, m0
	s_mov_b32 exec_hi, m0
	global_store_dwordx4 v[116:117], v[86:89], off offset:512
	s_mov_b64 exec, -1
	s_cselect_b32 s17, s17, s38
	v_ashrrev_i32_e32 v99, 31, v98
	v_lshl_add_u64 v[86:87], v[74:75], 0, v[180:181]
	s_mul_hi_i32 s39, s17, 0x6000
	s_mulk_i32 s17, 0x6000
	v_readlane_b32 s28, v255, 25
	v_pk_fma_f32 v[96:97], v[96:97], v[144:145], v[112:113]
	v_pk_fma_f32 v[94:95], v[94:95], v[142:143], v[110:111]
	v_pk_fma_f32 v[92:93], v[92:93], v[140:141], v[108:109]
	v_pk_fma_f32 v[90:91], v[90:91], v[138:139], v[106:107]
	s_add_u32 s38, s28, s17
	v_readlane_b32 s17, v255, 27
	s_mov_b32 exec_lo, m0
	s_mov_b32 exec_hi, m0
	global_store_dwordx4 v[116:117], v[94:97], off
	global_store_dwordx4 v[116:117], v[90:93], off offset:64
	s_mov_b64 exec, -1
	s_addc_u32 s39, s17, s39
	v_or_b32_e32 v102, 16, v98
	s_movk_i32 s15, 0x7fff
	s_waitcnt vmcnt(7)
	v_pk_fma_f32 v[76:77], v[84:85], v[144:145], v[120:121]
	v_pk_fma_f32 v[74:75], v[82:83], v[142:143], v[118:119]
	v_cndmask_b32_e32 v82, v0, v98, vcc
	v_mov_b32_e32 v0, s35
	v_mov_b32_e32 v84, s31
	v_cndmask_b32_e32 v83, 0, v99, vcc
	v_cndmask_b32_e32 v85, v0, v84, vcc
	v_mov_b32_e32 v0, s34
	v_mov_b32_e32 v84, s30
	v_cndmask_b32_e32 v84, v0, v84, vcc
	v_lshlrev_b64 v[82:83], 12, v[82:83]
	s_cmp_eq_u32 s100, 2
	s_cselect_b64 exec, 0, -1
	global_store_dwordx4 v[86:87], v[74:77], off
	s_mov_b64 exec, -1
	s_waitcnt vmcnt(6)
;     __device__ __forceinline__ void operator()(const f32x4 (&acc)[2][2][4][2], const Unit& u, int wr, int wc, int fr, int fq) const {
;     ...
;                 for (int mp = 0; mp < 2; ++mp) {
;                 f32x4 xv[2][2][2];
; #pragma unroll
;                 for (int mm = 0; mm < 2; ++mm) { const int gr = grb + (2 * mp + mm) * 16 + fr;
;                     const float* xr = (gr < MP ? xin_p + (size_t)gr * DM : xin_s + (size_t)(gr - MP) * DM) + col0;
; #pragma unroll
;                     for (int bj = 0; bj < 2; ++bj)
; #pragma unroll
;                         for (int n = 0; n < 2; ++n) xv[mm][bj][n] = *(const f32x4*)(xr + bj * HALF + n * 16); }
; #pragma unroll
;                 for (int mm = 0; mm < 2; ++mm) { const int m = 2 * mp + mm; const int gr = grb + m * 16 + fr; float* orow = out + (size_t)gr * DM + col0;
; #pragma unroll
;                     for (int bj = 0; bj < 2; ++bj)
; #pragma unroll
;                         for (int n = 0; n < 2; ++n) *(f32x4*)(orow + bj * HALF + n * 16) = xv[mm][bj][n] + gv[bj][n] * acc[ai][bj][m][n]; }
	v_pk_fma_f32 v[72:73], v[72:73], v[136:137], v[128:129]
	v_pk_fma_f32 v[70:71], v[70:71], v[134:135], v[126:127]
	v_pk_fma_f32 v[76:77], v[80:81], v[140:141], v[124:125]
	v_pk_fma_f32 v[74:75], v[78:79], v[138:139], v[122:123]
	s_waitcnt vmcnt(5)
	v_pk_fma_f32 v[68:69], v[68:69], v[132:133], v[148:149]
	v_pk_fma_f32 v[66:67], v[66:67], v[130:131], v[146:147]
	v_lshl_add_u64 v[82:83], v[84:85], 0, v[82:83]
	s_cmp_eq_u32 s100, 2
	s_cselect_b64 exec, 0, -1
	global_store_dwordx4 v[86:87], v[74:77], off offset:64
	global_store_dwordx4 v[86:87], v[70:73], off offset:512
	global_store_dwordx4 v[86:87], v[66:69], off offset:576
	s_mov_b64 exec, -1
	v_lshl_add_u64 v[82:83], v[82:83], 0, v[180:181]
	v_cmp_lt_i32_e32 vcc, s15, v102
	v_lshl_add_u64 v[66:67], s[38:39], 0, v[180:181]
	global_load_dwordx4 v[78:81], v[66:67], off
	global_load_dwordx4 v[74:77], v[66:67], off offset:64
	global_load_dwordx4 v[70:73], v[66:67], off offset:512
	s_nop 0
	global_load_dwordx4 v[66:69], v[66:67], off offset:576
	s_nop 0
	global_load_dwordx4 v[94:97], v[82:83], off
	global_load_dwordx4 v[90:93], v[82:83], off offset:64
	global_load_dwordx4 v[86:89], v[82:83], off offset:512
	s_nop 0
	global_load_dwordx4 v[82:85], v[82:83], off offset:576
	s_and_saveexec_b64 s[38:39], vcc
	s_xor_b64 s[38:39], exec, s[38:39]
	v_add_u32_e32 v0, 0xffff8010, v98
	v_lshlrev_b64 v[100:101], 12, v[0:1]
	v_mov_b32_e32 v103, v1
	v_lshl_add_u64 v[104:105], s[34:35], 0, v[100:101]
	v_lshlrev_b64 v[100:101], 12, v[102:103]
	s_andn2_saveexec_b64 s[38:39], s[38:39]
	v_ashrrev_i32_e32 v103, 31, v102
	v_lshlrev_b64 v[100:101], 12, v[102:103]
	v_lshl_add_u64 v[104:105], s[30:31], 0, v[100:101]
	s_or_b64 exec, exec, s[38:39]
	v_lshl_add_u64 v[114:115], v[104:105], 0, v[180:181]
	global_load_dwordx4 v[102:105], v[114:115], off
	global_load_dwordx4 v[106:109], v[114:115], off offset:64
	global_load_dwordx4 v[110:113], v[114:115], off offset:512
	s_nop 0
	global_load_dwordx4 v[114:117], v[114:115], off offset:576
	v_lshlrev_b64 v[118:119], 12, v[98:99]
	s_waitcnt vmcnt(4)
	v_pk_fma_f32 v[82:83], v[50:51], v[66:67], v[82:83]
	v_or_b32_e32 v50, 32, v98
	s_mov_b32 s15, 0x8000
	v_pk_fma_f32 v[54:55], v[54:55], v[70:71], v[86:87]
	v_add_u32_e32 v0, 0xffff8020, v98
	v_lshl_add_u64 v[86:87], s[24:25], 0, v[118:119]
	v_ashrrev_i32_e32 v51, 31, v50
	v_cmp_gt_i32_e32 vcc, s15, v50
	v_pk_fma_f32 v[64:65], v[64:65], v[80:81], v[96:97]
	v_pk_fma_f32 v[62:63], v[62:63], v[78:79], v[94:95]
	v_pk_fma_f32 v[60:61], v[60:61], v[76:77], v[92:93]
	v_pk_fma_f32 v[58:59], v[58:59], v[74:75], v[90:91]
	v_pk_fma_f32 v[56:57], v[56:57], v[72:73], v[88:89]
	v_mov_b32_e32 v90, s35
	v_mov_b32_e32 v91, s31
	v_mov_b32_e32 v92, s34
	v_mov_b32_e32 v93, s30
	v_lshl_add_u64 v[86:87], v[86:87], 0, v[180:181]
	v_cndmask_b32_e32 v89, 0, v51, vcc
	v_cndmask_b32_e32 v88, v0, v50, vcc
	v_pk_fma_f32 v[84:85], v[52:53], v[68:69], v[84:85]
	v_lshl_add_u64 v[52:53], s[24:25], 0, v[100:101]
	v_cndmask_b32_e32 v91, v90, v91, vcc
	v_cndmask_b32_e32 v90, v92, v93, vcc
	s_cmp_eq_u32 s100, 1
	s_cselect_b64 exec, 0, -1
	global_store_dwordx4 v[86:87], v[62:65], off
	global_store_dwordx4 v[86:87], v[58:61], off offset:64
	global_store_dwordx4 v[86:87], v[54:57], off offset:512
	global_store_dwordx4 v[86:87], v[82:85], off offset:576
	s_mov_b64 exec, -1
	v_lshl_add_u64 v[52:53], v[52:53], 0, v[180:181]
	v_lshlrev_b64 v[54:55], 12, v[88:89]
	v_lshl_add_u64 v[54:55], v[90:91], 0, v[54:55]
	v_lshl_add_u64 v[54:55], v[54:55], 0, v[180:181]
	s_movk_i32 s15, 0x7fff
	s_waitcnt vmcnt(7)
	v_pk_fma_f32 v[48:49], v[48:49], v[80:81], v[104:105]
	v_pk_fma_f32 v[46:47], v[46:47], v[78:79], v[102:103]
	s_waitcnt vmcnt(6)
; #define PG8_BAR __builtin_amdgcn_s_barrier()
; template <class Epi, bool GS = false>
; __device__ __forceinline__ void gemm_phase(LAS unsigned char* lds, const Gemm g, const StaticOrder& S, const Epi& E, const int tid) {
;     ...
;         if (!has_next) break;
; #pragma unroll
;         for (int a = 0; a < 2; ++a)
; #pragma unroll
;             for (int b = 0; b < 2; ++b)
; #pragma unroll
;                 for (int m = 0; m < 4; ++m)
; #pragma unroll
;                     for (int n = 0; n < 2; ++n) acc[a][b][m][n] = (f32x4){0.f, 0.f, 0.f, 0.f};
;         cur = nxt; cA = nA; cB = nB; ++ui;
;         if (wr == 1) PG8_BAR;
;     __device__ __forceinline__ void operator()(const f32x4 (&acc)[2][2][4][2], const Unit& u, int wr, int wc, int fr, int fq) const {
;     ...
;                 for (int mm = 0; mm < 2; ++mm) { const int gr = grb + (2 * mp + mm) * 16 + fr;
;                     const float* xr = (gr < MP ? xin_p + (size_t)gr * DM : xin_s + (size_t)(gr - MP) * DM) + col0;
; #pragma unroll
;                     for (int bj = 0; bj < 2; ++bj)
; #pragma unroll
;                         for (int n = 0; n < 2; ++n) xv[mm][bj][n] = *(const f32x4*)(xr + bj * HALF + n * 16); }
; #pragma unroll
;                 for (int mm = 0; mm < 2; ++mm) { const int m = 2 * mp + mm; const int gr = grb + m * 16 + fr; float* orow = out + (size_t)gr * DM + col0;
; #pragma unroll
;                     for (int bj = 0; bj < 2; ++bj)
; #pragma unroll
;                         for (int n = 0; n < 2; ++n) *(f32x4*)(orow + bj * HALF + n * 16) = xv[mm][bj][n] + gv[bj][n] * acc[ai][bj][m][n]; }
	v_pk_fma_f32 v[44:45], v[44:45], v[76:77], v[108:109]
	v_pk_fma_f32 v[42:43], v[42:43], v[74:75], v[106:107]
	s_waitcnt vmcnt(5)
	v_pk_fma_f32 v[40:41], v[40:41], v[72:73], v[112:113]
	v_pk_fma_f32 v[38:39], v[38:39], v[70:71], v[110:111]
	s_waitcnt vmcnt(4)
	v_pk_fma_f32 v[36:37], v[36:37], v[68:69], v[116:117]
	v_pk_fma_f32 v[34:35], v[34:35], v[66:67], v[114:115]
	s_cmp_eq_u32 s100, 1
	s_cselect_b64 exec, 0, -1
	global_store_dwordx4 v[52:53], v[46:49], off
	global_store_dwordx4 v[52:53], v[42:45], off offset:64
	global_store_dwordx4 v[52:53], v[38:41], off offset:512
	global_store_dwordx4 v[52:53], v[34:37], off offset:576
	s_mov_b64 exec, -1
	global_load_dwordx4 v[46:49], v[54:55], off
	s_nop 0
	global_load_dwordx4 v[42:45], v[54:55], off offset:64
	global_load_dwordx4 v[38:41], v[54:55], off offset:512
	global_load_dwordx4 v[34:37], v[54:55], off offset:576
	v_or_b32_e32 v54, 48, v98
	v_cmp_lt_i32_e32 vcc, s15, v54
	s_and_saveexec_b64 s[38:39], vcc
	s_xor_b64 s[38:39], exec, s[38:39]
	v_add_u32_e32 v0, 0xffff8030, v98
	v_lshlrev_b64 v[52:53], 12, v[0:1]
	v_mov_b32_e32 v55, v1
	v_lshl_add_u64 v[56:57], s[34:35], 0, v[52:53]
	v_lshlrev_b64 v[52:53], 12, v[54:55]
	s_andn2_saveexec_b64 s[38:39], s[38:39]
	v_ashrrev_i32_e32 v55, 31, v54
	v_lshlrev_b64 v[52:53], 12, v[54:55]
	v_lshl_add_u64 v[56:57], s[30:31], 0, v[52:53]
	s_or_b64 exec, exec, s[38:39]
	v_lshl_add_u64 v[82:83], v[56:57], 0, v[180:181]
	global_load_dwordx4 v[54:57], v[82:83], off
	global_load_dwordx4 v[58:61], v[82:83], off offset:64
	global_load_dwordx4 v[62:65], v[82:83], off offset:512
	s_nop 0
	global_load_dwordx4 v[82:85], v[82:83], off offset:576
	v_lshlrev_b64 v[50:51], 12, v[50:51]
	s_waitcnt vmcnt(4)
	v_pk_fma_f32 v[20:21], v[20:21], v[68:69], v[36:37]
	v_pk_fma_f32 v[18:19], v[18:19], v[66:67], v[34:35]
	v_lshl_add_u64 v[34:35], s[24:25], 0, v[52:53]
	v_lshl_add_u64 v[36:37], s[24:25], 0, v[50:51]
	v_pk_fma_f32 v[32:33], v[32:33], v[80:81], v[48:49]
	v_pk_fma_f32 v[30:31], v[30:31], v[78:79], v[46:47]
	v_lshl_add_u64 v[34:35], v[34:35], 0, v[180:181]
	v_lshl_add_u64 v[36:37], v[36:37], 0, v[180:181]
	s_andn2_b64 vcc, exec, s[4:5]
	s_mov_b64 s[4:5], -1
	v_pk_fma_f32 v[28:29], v[28:29], v[76:77], v[44:45]
	v_pk_fma_f32 v[26:27], v[26:27], v[74:75], v[42:43]
	v_pk_fma_f32 v[24:25], v[24:25], v[72:73], v[40:41]
	v_pk_fma_f32 v[22:23], v[22:23], v[70:71], v[38:39]
	s_cmp_eq_u32 s100, 1
	s_cselect_b64 exec, 0, -1
	global_store_dwordx4 v[36:37], v[30:33], off
	global_store_dwordx4 v[36:37], v[26:29], off offset:64
	global_store_dwordx4 v[36:37], v[22:25], off offset:512
	global_store_dwordx4 v[36:37], v[18:21], off offset:576
	s_mov_b64 exec, -1
	s_waitcnt vmcnt(7)
	v_pk_fma_f32 v[16:17], v[16:17], v[80:81], v[56:57]
	v_pk_fma_f32 v[14:15], v[14:15], v[78:79], v[54:55]
	s_waitcnt vmcnt(6)
	v_pk_fma_f32 v[12:13], v[12:13], v[76:77], v[60:61]
	v_pk_fma_f32 v[10:11], v[10:11], v[74:75], v[58:59]
	s_waitcnt vmcnt(5)
	v_pk_fma_f32 v[8:9], v[8:9], v[72:73], v[64:65]
	v_pk_fma_f32 v[6:7], v[6:7], v[70:71], v[62:63]
	s_waitcnt vmcnt(4)
	v_pk_fma_f32 v[4:5], v[4:5], v[68:69], v[84:85]
	v_pk_fma_f32 v[2:3], v[2:3], v[66:67], v[82:83]
	s_cmp_eq_u32 s100, 1
	s_cselect_b64 exec, 0, -1
	global_store_dwordx4 v[34:35], v[14:17], off
	global_store_dwordx4 v[34:35], v[10:13], off offset:64
	global_store_dwordx4 v[34:35], v[6:9], off offset:512
	global_store_dwordx4 v[34:35], v[2:5], off offset:576
	s_mov_b64 exec, -1
	s_cbranch_vccnz .LBB0_777
	s_andn2_b64 vcc, exec, s[6:7]
	s_cbranch_vccnz .LBB0_776
	s_barrier
	s_branch .LBB0_776

;     __device__ __forceinline__ const char* Ap(int part) const { return (const char*)A0 + (long)(part == 1) * ((const char*)A1 - (const char*)A0) + (long)(part == 2) * ((const char*)A2 - (const char*)A0); }
;     __device__ __forceinline__ const char* Bp(int part) const { return (const char*)B0 + (long)(part == 1) * ((const char*)B1 - (const char*)B0) + (long)(part == 2) * ((const char*)B2 - (const char*)B0); }
; #define PG8_WAIT_V(n) asm volatile("s_waitcnt vmcnt(" #n ")" ::: "memory")
; template <class Epi, bool GS = false>
; __device__ __forceinline__ void gemm_phase(LAS unsigned char* lds, const Gemm g, const StaticOrder& S, const Epi& E, const int tid) {
;     const int wid = __builtin_amdgcn_readfirstlane(tid >> 6), lane = tid & 63, wr = wid >> 2, wc = wid & 3, fr = lane & 15, fq = lane >> 4;
;     unsigned voffA[2], voffB[2];
; #pragma unroll
;     for (int i = 0; i < 2; ++i) { int R, C; stage_rc(tid * 16 + i * 8192, R, C); const int Rb = Epi::PERM ? ((R & ~31) + perm32(R & 31)) : R;
;         voffA[i] = (unsigned)(R * g.lda + C) * 2u; voffB[i] = (unsigned)(Rb * g.ldb + C) * 2u; }
;     const size_t kstep = (size_t)(BK * 2);
;     const size_t hstepA = (size_t)HALF * g.lda * 2, hstepB = (size_t)HALF * g.ldb * 2;
;     const size_t tstepA = 2 * hstepA, tstepB = 2 * hstepB;
;     const unsigned ldsw = (unsigned)wid * 1024u;
;     const int aoff = lds_byte(wr * 64 + fr, fq * 8), boff = lds_byte(wc * 32 + fr, fq * 8);
;     ...
;     Unit cur, nxt; int ui = 0;
;     if (!S.next(0, cur)) return;
;     f32x4 acc[2][2][4][2];
; #pragma unroll
;     for (int a = 0; a < 2; ++a)
; #pragma unroll
;         for (int b = 0; b < 2; ++b)
; #pragma unroll
;             for (int m = 0; m < 4; ++m)
; #pragma unroll
;                 for (int n = 0; n < 2; ++n) acc[a][b][m][n] = (f32x4){0.f, 0.f, 0.f, 0.f};
;     bf16x8 At[4][2], B0[2][2], B1[2][2];
;     const char* cA = g.Ap(cur.part) + (size_t)cur.pm * tstepA; const char* cB = g.Bp(cur.part) + (size_t)cur.pn * tstepB;
;     PG8_STAGE(PG8_SB(0, 0), cB, voffB); PG8_STAGE(PG8_SB(0, 1), cB + hstepB, voffB); PG8_STAGE(PG8_SA(0, 0), cA, voffA); PG8_STAGE(PG8_SA(0, 1), cA + hstepA, voffA);
;     if (wr == 1) PG8_BAR;
;     PG8_WAIT_V(2); PG8_BAR;
;     PG8_STAGE(PG8_SB(1, 0), cB + kstep, voffB); PG8_STAGE(PG8_SA(1, 0), cA + kstep, voffA); PG8_STAGE(PG8_SB(1, 1), cB + hstepB + kstep, voffB);
;     PG8_WAIT_V(6); PG8_BAR;
.LBB0_980:
	s_or_b64 exec, exec, s[4:5]
	v_readlane_b32 s2, v254, 2
	v_mov_b32_e32 v13, v166
	v_readlane_b32 s3, v254, 3
	s_waitcnt lgkmcnt(0)
	s_barrier
	s_andn2_b64 vcc, exec, s[2:3]
	v_readfirstlane_b32 s4, v13
	s_cbranch_vccnz .LBB0_1016
	s_mov_b32 s100, 0
	s_mov_b32 s101, 0
	v_lshlrev_b32_e32 v0, 4, v13
	v_add_u32_e32 v2, 0x2000, v0
	v_ashrrev_i32_e32 v3, 31, v2
	v_lshrrev_b32_e32 v3, 22, v3
	v_add_u32_e32 v3, v2, v3
	v_ashrrev_i32_e32 v6, 10, v3
	v_mul_i32_i24_e32 v3, 0x400, v6
	v_sub_u32_e32 v2, v2, v3
	v_lshrrev_b32_e32 v3, 4, v2
	v_bitop3_b32 v2, v3, v2, 32 bitop3:0x6c
	v_ashrrev_i32_e32 v3, 31, v2
	v_lshrrev_b32_e32 v3, 26, v3
	v_add_u32_e32 v3, v2, v3
	v_ashrrev_i32_e32 v7, 6, v3
	v_and_b32_e32 v3, 0xc0, v3
	v_sub_u32_e32 v2, v2, v3
	v_ashrrev_i16_sdwa v2, v196, sext(v2) dst_sel:DWORD dst_unused:UNUSED_PAD src0_sel:DWORD src1_sel:BYTE_0
	v_lshlrev_b32_e32 v4, 3, v6
	v_bfe_i32 v9, v2, 0, 16
	v_bfe_i32 v2, v13, 27, 1
	v_and_b32_e32 v4, 0xfffff0, v4
	v_lshrrev_b32_e32 v2, 22, v2
	v_add_u32_e32 v4, v7, v4
	s_movk_i32 s7, 0xb00
	v_lshlrev_b32_e32 v5, 5, v6
	v_add_u32_e32 v2, v0, v2
	v_mul_lo_u32 v4, v4, s7
	v_and_b32_e32 v8, 32, v5
	v_and_b32_e32 v2, 0xfffffc00, v2
	v_or_b32_e32 v4, v4, v8
	v_sub_u32_e32 v0, v0, v2
	v_add_lshl_u32 v162, v4, v9, 1
	v_lshrrev_b32_e32 v2, 4, v0
	v_ashrrev_i32_e32 v4, 31, v13
	v_bitop3_b32 v2, v2, v0, 32 bitop3:0x6c
	v_lshrrev_b32_e32 v4, 26, v4
	v_ashrrev_i32_e32 v0, 31, v2
	v_add_u32_e32 v4, v13, v4
	v_lshrrev_b32_e32 v0, 26, v0
	v_ashrrev_i32_e32 v10, 6, v4
	v_readlane_b32 s2, v255, 20
	v_add_u32_e32 v3, v2, v0
	v_lshlrev_b32_e32 v4, 3, v10
	s_add_u32 s2, s2, 0x2480000
	v_readlane_b32 s3, v255, 22
	v_ashrrev_i32_e32 v0, 6, v3
	v_and_b32_e32 v4, 0xfffff0, v4
	s_addc_u32 s3, s3, 0
	s_ashr_i32 s5, s4, 6
	v_add_u32_e32 v4, v0, v4
	v_and_b32_e32 v3, 0xc0, v3
	v_readlane_b32 s8, v254, 16
	s_ashr_i32 s6, s4, 8
	s_lshl_b32 s10, s5, 10
	v_mul_lo_u32 v4, v4, s7
	v_lshlrev_b32_e32 v5, 5, v10
	v_sub_u32_e32 v2, v2, v3
	s_mul_i32 s7, s8, 0x160000
	v_and_b32_e32 v11, 32, v5
	v_ashrrev_i16_sdwa v2, v196, sext(v2) dst_sel:DWORD dst_unused:UNUSED_PAD src0_sel:DWORD src1_sel:BYTE_0
	s_add_u32 s22, s2, s7
	s_mul_hi_i32 s7, s8, 0x160000
	v_or_b32_e32 v4, v4, v11
	v_bfe_i32 v12, v2, 0, 16
	s_addc_u32 s23, s3, s7
	s_add_i32 s36, s10, 0
	v_add_lshl_u32 v164, v4, v12, 1
	s_add_i32 m0, s36, 0x10000
	v_mov_b32_e32 v165, v1
	global_load_lds_dwordx4 v164, s[22:23]
	s_add_i32 m0, s36, 0x12000
	s_add_u32 s8, s22, 0xb0000
	global_load_lds_dwordx4 v162, s[22:23]
	s_addc_u32 s9, s23, 0
	s_add_i32 m0, s36, 0x14000
	s_add_i32 s37, s36, 0x2000
	global_load_lds_dwordx4 v164, s[8:9]
	s_add_i32 m0, s36, 0x16000
	s_add_i32 s38, s36, 0x4000
	global_load_lds_dwordx4 v162, s[8:9]
	v_readlane_b32 s8, v254, 19
	s_mov_b32 m0, s36
	v_readlane_b32 s9, v254, 20
	s_add_i32 s39, s36, 0x6000
	v_mov_b32_e32 v163, v1
	s_cmp_eq_u32 s6, 1
	v_lshl_add_u64 v[2:3], s[22:23], 0, v[164:165]
	v_lshl_add_u64 v[4:5], s[22:23], 0, v[162:163]
	global_load_lds_dwordx4 v164, s[8:9]
	s_mov_b32 m0, s37
	s_nop 0
	global_load_lds_dwordx4 v162, s[8:9]
	v_readlane_b32 s8, v254, 21
	s_mov_b32 m0, s38
	v_readlane_b32 s9, v254, 22
	s_nop 4
	global_load_lds_dwordx4 v164, s[8:9]
	s_mov_b32 m0, s39
	s_nop 0
	global_load_lds_dwordx4 v162, s[8:9]
	s_cselect_b64 s[8:9], -1, 0
	s_cmp_lg_u32 s6, 1
	s_cbranch_scc1 .LBB0_983
	s_barrier

;     __device__ __forceinline__ const char* Ap(int part) const { return (const char*)A0 + (long)(part == 1) * ((const char*)A1 - (const char*)A0) + (long)(part == 2) * ((const char*)A2 - (const char*)A0); }
;     __device__ __forceinline__ const char* Bp(int part) const { return (const char*)B0 + (long)(part == 1) * ((const char*)B1 - (const char*)B0) + (long)(part == 2) * ((const char*)B2 - (const char*)B0); }
;     __device__ __forceinline__ bool next(int i, Unit& u) const {
;         const int r = i / np; u.part = i - r * np;
;         long L = (long)r * G + c;
;         if (L >= split_from) { const long Ls = L - split_from; if (Ls >= 2L * (nwg - split_from)) return false; L = split_from + (Ls >> 1); u.part = 1 + (int)(Ls & 1); }
;         if (L >= nwg) return false;
;         int wgid = (int)L; { const int q = nwg / NXCD, rr = nwg % NXCD, xcd = wgid % NXCD, off = wgid / NXCD; wgid = (xcd < rr ? xcd * (q + 1) : rr * (q + 1) + (xcd - rr) * q) + off; }
;         const int nig = WGM * nN, gid = wgid / nig, fm = gid * WGM, gsz = (nM - fm) < WGM ? (nM - fm) : WGM;
;         u.pm = fm + ((wgid % nig) % gsz); u.pn = (wgid % nig) / gsz; return true;
;     }
; template <class Epi, bool GS = false>
; __device__ __forceinline__ void gemm_phase(LAS unsigned char* lds, const Gemm g, const StaticOrder& S, const Epi& E, const int tid) {
;     ...
;     for (;;) {
;         const bool has_next = S.next(ui + 1, nxt);
;         const char* nA = has_next ? g.Ap(nxt.part) + (size_t)nxt.pm * tstepA : cA; const char* nB = has_next ? g.Bp(nxt.part) + (size_t)nxt.pn * tstepB : cB;
.LBB0_985:
	s_mov_b32 s100, s101
	s_andn2_b64 vcc, exec, s[4:5]
	s_mov_b32 s49, s46
	s_mov_b32 s48, s47
	s_mov_b64 s[22:23], s[16:17]
	s_mov_b64 s[20:21], s[6:7]
	s_cbranch_vccz .LBB0_1015
.LBB0_986:
	s_add_i32 s45, s45, 1
	v_readlane_b32 s4, v253, 53
	v_readlane_b32 s6, v252, 0
	s_mul_i32 s4, s45, s4
	v_readlane_b32 s7, v252, 1
	s_mul_hi_u32 s5, s45, s6
	s_add_i32 s5, s5, s4
	s_mul_i32 s4, s45, s6
	v_readlane_b32 s6, v254, 38
	v_readlane_b32 s7, v254, 39
	s_add_u32 s4, s4, s6
	s_addc_u32 s5, s5, s7
	s_mov_b32 s101, 0
	s_cmp_lt_u32 s4, 0x200
	s_cbranch_scc1 .Ltail9_ns
	s_sub_i32 s16, s4, 0x200
	s_and_b32 s101, s16, 1
	s_add_i32 s101, s101, 1
	s_lshr_b32 s17, s16, 1
	s_add_i32 s4, s17, 0x200
	s_cmp_lt_u32 s16, 64
	s_cselect_b32 s4, s4, 0x7fff
.Ltail9_ns:
	v_mov_b64_e32 v[2:3], 0x220
	v_cmp_gt_i64_e32 vcc, s[4:5], v[174:175]
	v_cmp_lt_i64_e64 s[6:7], s[4:5], v[2:3]
	s_cbranch_vccnz .LBB0_988
	s_ashr_i32 s5, s4, 31
	s_lshr_b32 s5, s5, 29
	s_add_i32 s5, s4, s5
	s_ashr_i32 s16, s5, 3
	s_and_b32 s5, s5, -8
	s_sub_i32 s4, s4, s5
	s_cmp_lt_i32 s4, 0
	s_movk_i32 s5, 0x45
	s_cselect_b32 s5, s5, 0x44
	s_mul_i32 s4, s4, s5
	s_add_i32 s4, s4, s16
	s_ashr_i32 s5, s4, 31
	s_lshr_b32 s5, s5, 27
	s_add_i32 s5, s4, s5
	s_ashr_i32 s16, s5, 5
	s_lshl_b32 s16, s16, 3
	s_sub_i32 s17, 0x88, s16
	s_min_i32 s17, s17, 8
	s_abs_i32 s30, s17
	v_cvt_f32_u32_e32 v0, s30
	s_sub_i32 s34, 0, s30
	s_andn2_b32 s5, s5, 31
	s_sub_i32 s4, s4, s5
	v_rcp_iflag_f32_e32 v0, v0
	s_abs_i32 s5, s4
	s_xor_b32 s31, s4, s17
	s_ashr_i32 s31, s31, 31
	v_mul_f32_e32 v0, 0x4f7ffffe, v0
	v_cvt_u32_f32_e32 v0, v0
	s_nop 0
	v_readfirstlane_b32 s35, v0
	s_mul_i32 s34, s34, s35
	s_mul_hi_u32 s34, s35, s34
	s_add_i32 s35, s35, s34
	s_mul_hi_u32 s34, s5, s35
	s_mul_i32 s35, s34, s30
	s_sub_i32 s5, s5, s35
	s_add_i32 s46, s34, 1
	s_sub_i32 s35, s5, s30
	s_cmp_ge_u32 s5, s30
	s_cselect_b32 s34, s46, s34
	s_cselect_b32 s5, s35, s5
	s_add_i32 s35, s34, 1
	s_cmp_ge_u32 s5, s30
	s_cselect_b32 s5, s35, s34
	s_xor_b32 s5, s5, s31
	s_sub_i32 s46, s5, s31
	s_mul_i32 s5, s46, s17
	s_sub_i32 s4, s4, s5
	s_add_i32 s47, s16, s4

; #define PG8_STAGE(bufoff, gbase, voff) do { _Pragma("unroll") for (int _i = 0; _i < 2; ++_i) \
;         __builtin_amdgcn_global_load_lds((const unsigned*)((const char*)(gbase) + (voff)[_i]), (LAS unsigned*)(lds + (bufoff) + ldsw + _i * 8192), 16, 0, 0); } while (0)
; #define PG8_LDA(dst, b, h) do { _Pragma("unroll") for (int m = 0; m < 4; ++m) _Pragma("unroll") for (int k = 0; k < 2; ++k) dst[m][k] = *(const LAS bf16x8*)(lds + PG8_SA(b, h) + aoff + m * 2048 + k * 1024); } while (0)
; #define PG8_LDB(dst, b, h) do { _Pragma("unroll") for (int n = 0; n < 2; ++n) _Pragma("unroll") for (int k = 0; k < 2; ++k) dst[n][k] = *(const LAS bf16x8*)(lds + PG8_SB(b, h) + boff + n * 2048 + k * 1024); } while (0)
; #define PG8_MMA(ai, bj, At, Bt) do { __builtin_amdgcn_s_setprio(1); _Pragma("unroll") for (int m = 0; m < 4; ++m) _Pragma("unroll") for (int n = 0; n < 2; ++n) _Pragma("unroll") for (int k = 0; k < 2; ++k) \
;         acc[ai][bj][m][n] = __builtin_amdgcn_mfma_f32_16x16x32_bf16(Bt[n][k], At[m][k], acc[ai][bj][m][n], 0, 0, 0); __builtin_amdgcn_s_setprio(0); } while (0)
; #define PG8_WAIT_V(n) asm volatile("s_waitcnt vmcnt(" #n ")" ::: "memory")
; #define PG8_WAIT_L(n) asm volatile("s_waitcnt lgkmcnt(" #n ")" ::: "memory")
; #define PG8_BAR __builtin_amdgcn_s_barrier()
; #define PG8_SCHED __builtin_amdgcn_sched_barrier(0)
; template <class Epi, bool GS = false>
; __device__ __forceinline__ void gemm_phase(LAS unsigned char* lds, const Gemm g, const StaticOrder& S, const Epi& E, const int tid) {
;     ...
;         for (int t = tg; t < tg + seg; t += 2) {
;             const bool last = (t == nt - 2);
;             const char* a1 = cA + (size_t)(t + 1) * kstep;
;             const char* a2 = last ? nA : cA + (size_t)(t + 2) * kstep; const char* b2 = last ? nB : cB + (size_t)(t + 2) * kstep;
;             const char* a3 = a2 + kstep; const char* b3 = b2 + kstep;
;             PG8_LDB(B0, 0, 0); PG8_LDB(B1, 0, 1); PG8_SCHED; PG8_LDA(At, 0, 0); PG8_STAGE(PG8_SA(1, 1), a1 + hstepA, voffA);
;             PG8_WAIT_V(8); PG8_WAIT_L(0); PG8_BAR; PG8_MMA(0, 0, At, B0); PG8_MMA(0, 1, At, B1); PG8_BAR; PG8_SCHED;
;             PG8_LDA(At, 0, 1); PG8_STAGE(PG8_SB(0, 0), b2, voffB); PG8_STAGE(PG8_SB(0, 1), b2 + hstepB, voffB); PG8_STAGE(PG8_SA(0, 0), a2, voffA);
;             PG8_WAIT_V(8); PG8_WAIT_L(0); PG8_BAR; PG8_MMA(1, 0, At, B0); PG8_MMA(1, 1, At, B1); PG8_BAR; PG8_SCHED;
.LBB0_993:
	s_add_u32 s22, s20, 0x100
	s_addc_u32 s23, s21, 0
	s_add_i32 s53, 0, 0x10000
	s_cmp_eq_u32 s52, 40
	s_cselect_b32 s35, s7, s23
	s_cselect_b32 s34, s6, s22
	v_add_u32_e32 v0, s53, v190
	s_cselect_b32 s31, s17, s51
	s_cselect_b32 s30, s16, s50
	s_add_i32 s54, 0, 0x14000
	ds_read_b128 v[130:133], v0
	ds_read_b128 v[134:137], v0 offset:1024
	ds_read_b128 v[138:141], v0 offset:2048
	ds_read_b128 v[142:145], v0 offset:3072
	v_add_u32_e32 v0, s54, v190
	ds_read_b128 v[146:149], v0
	ds_read_b128 v[150:153], v0 offset:1024
	ds_read_b128 v[154:157], v0 offset:2048
	ds_read_b128 v[158:161], v0 offset:3072
	v_lshl_add_u64 v[188:189], s[20:21], 0, v[176:177]
	s_add_i32 m0, s36, 0xc000
	ds_read_b128 v[180:183], v192
	ds_read_b128 v[184:187], v192 offset:1024
	ds_read_b128 v[216:219], v192 offset:2048
	ds_read_b128 v[220:223], v192 offset:3072
	ds_read_b128 v[224:227], v192 offset:4096
	ds_read_b128 v[228:231], v192 offset:5120
	ds_read_b128 v[232:235], v192 offset:6144
	ds_read_b128 v[236:239], v192 offset:7168
	global_load_lds_dwordx4 v[188:189], off
	v_lshl_add_u64 v[188:189], s[20:21], 0, v[178:179]
	s_add_i32 m0, s36, 0xe000
	s_nop 0
	global_load_lds_dwordx4 v[188:189], off
	s_waitcnt vmcnt(8)
	s_waitcnt lgkmcnt(0)
	s_barrier
	s_setprio 1
	s_waitcnt lgkmcnt(0)
	s_cmp_eq_u32 s100, 2
	s_cbranch_scc1 .Ltail9_skip0
	v_mfma_f32_16x16x32_bf16 v[126:129], v[130:133], v[180:183], v[126:129]
	v_mfma_f32_16x16x32_bf16 v[122:125], v[138:141], v[180:183], v[122:125]
	v_mfma_f32_16x16x32_bf16 v[110:113], v[130:133], v[216:219], v[110:113]
	v_mfma_f32_16x16x32_bf16 v[106:109], v[138:141], v[216:219], v[106:109]
	v_mfma_f32_16x16x32_bf16 v[94:97], v[130:133], v[224:227], v[94:97]
	v_mfma_f32_16x16x32_bf16 v[90:93], v[138:141], v[224:227], v[90:93]
	v_mfma_f32_16x16x32_bf16 v[78:81], v[130:133], v[232:235], v[78:81]
	v_mfma_f32_16x16x32_bf16 v[74:77], v[138:141], v[232:235], v[74:77]
	v_mfma_f32_16x16x32_bf16 v[126:129], v[134:137], v[184:187], v[126:129]
	v_mfma_f32_16x16x32_bf16 v[122:125], v[142:145], v[184:187], v[122:125]
	v_mfma_f32_16x16x32_bf16 v[110:113], v[134:137], v[220:223], v[110:113]
	v_mfma_f32_16x16x32_bf16 v[106:109], v[142:145], v[220:223], v[106:109]
	v_mfma_f32_16x16x32_bf16 v[94:97], v[134:137], v[228:231], v[94:97]
	v_mfma_f32_16x16x32_bf16 v[90:93], v[142:145], v[228:231], v[90:93]
	v_mfma_f32_16x16x32_bf16 v[78:81], v[134:137], v[236:239], v[78:81]
	v_mfma_f32_16x16x32_bf16 v[74:77], v[142:145], v[236:239], v[74:77]
	s_setprio 0
	s_setprio 1
	v_mfma_f32_16x16x32_bf16 v[118:121], v[146:149], v[180:183], v[118:121]
	v_mfma_f32_16x16x32_bf16 v[114:117], v[154:157], v[180:183], v[114:117]
	v_mfma_f32_16x16x32_bf16 v[102:105], v[146:149], v[216:219], v[102:105]
	v_mfma_f32_16x16x32_bf16 v[98:101], v[154:157], v[216:219], v[98:101]
	v_mfma_f32_16x16x32_bf16 v[86:89], v[146:149], v[224:227], v[86:89]
	v_mfma_f32_16x16x32_bf16 v[82:85], v[154:157], v[224:227], v[82:85]
	v_mfma_f32_16x16x32_bf16 v[70:73], v[146:149], v[232:235], v[70:73]
	v_mfma_f32_16x16x32_bf16 v[66:69], v[154:157], v[232:235], v[66:69]
	v_mfma_f32_16x16x32_bf16 v[118:121], v[150:153], v[184:187], v[118:121]
	v_mfma_f32_16x16x32_bf16 v[114:117], v[158:161], v[184:187], v[114:117]
	v_mfma_f32_16x16x32_bf16 v[102:105], v[150:153], v[220:223], v[102:105]
	v_mfma_f32_16x16x32_bf16 v[98:101], v[158:161], v[220:223], v[98:101]
	v_mfma_f32_16x16x32_bf16 v[86:89], v[150:153], v[228:231], v[86:89]
	v_mfma_f32_16x16x32_bf16 v[82:85], v[158:161], v[228:231], v[82:85]
	v_mfma_f32_16x16x32_bf16 v[70:73], v[150:153], v[236:239], v[70:73]
	v_mfma_f32_16x16x32_bf16 v[66:69], v[158:161], v[236:239], v[66:69]
	s_setprio 0
.Ltail9_skip0:
	s_setprio 0
	s_barrier
	s_add_i32 s20, s53, s10
	v_lshl_add_u64 v[188:189], s[30:31], 0, v[164:165]
	s_mov_b32 m0, s20
	ds_read_b128 v[180:183], v192 offset:16384
	ds_read_b128 v[184:187], v192 offset:17408
	ds_read_b128 v[216:219], v192 offset:18432
	ds_read_b128 v[220:223], v192 offset:19456
	ds_read_b128 v[224:227], v192 offset:20480
	ds_read_b128 v[228:231], v192 offset:21504
	ds_read_b128 v[232:235], v192 offset:22528
	ds_read_b128 v[236:239], v192 offset:23552
	global_load_lds_dwordx4 v[188:189], off
	s_add_i32 m0, s20, 0x2000
	s_add_u32 s20, s30, 0xb0000
	v_lshl_add_u64 v[194:195], s[30:31], 0, v[162:163]
	s_addc_u32 s21, s31, 0
	s_add_i32 s53, s54, s10
	global_load_lds_dwordx4 v[194:195], off
	v_lshl_add_u64 v[240:241], s[20:21], 0, v[164:165]
	s_mov_b32 m0, s53
	v_lshl_add_u64 v[242:243], s[34:35], 0, v[162:163]
	global_load_lds_dwordx4 v[240:241], off
	v_lshl_add_u64 v[240:241], s[20:21], 0, v[162:163]
	s_add_i32 m0, s53, 0x2000
	s_nop 0
	global_load_lds_dwordx4 v[240:241], off
	v_lshl_add_u64 v[240:241], s[34:35], 0, v[164:165]
	s_mov_b32 m0, s36
	s_nop 0
	global_load_lds_dwordx4 v[240:241], off
	s_mov_b32 m0, s37
	s_nop 0
	global_load_lds_dwordx4 v[242:243], off
	s_waitcnt vmcnt(8)
	s_waitcnt lgkmcnt(0)
	s_barrier
	s_setprio 1
	s_waitcnt lgkmcnt(0)
	s_cmp_eq_u32 s100, 1
	s_cbranch_scc1 .Ltail9_skip1
; #define PG8_STAGE(bufoff, gbase, voff) do { _Pragma("unroll") for (int _i = 0; _i < 2; ++_i) \
;         __builtin_amdgcn_global_load_lds((const unsigned*)((const char*)(gbase) + (voff)[_i]), (LAS unsigned*)(lds + (bufoff) + ldsw + _i * 8192), 16, 0, 0); } while (0)
; #define PG8_LDA(dst, b, h) do { _Pragma("unroll") for (int m = 0; m < 4; ++m) _Pragma("unroll") for (int k = 0; k < 2; ++k) dst[m][k] = *(const LAS bf16x8*)(lds + PG8_SA(b, h) + aoff + m * 2048 + k * 1024); } while (0)
; #define PG8_LDB(dst, b, h) do { _Pragma("unroll") for (int n = 0; n < 2; ++n) _Pragma("unroll") for (int k = 0; k < 2; ++k) dst[n][k] = *(const LAS bf16x8*)(lds + PG8_SB(b, h) + boff + n * 2048 + k * 1024); } while (0)
; #define PG8_MMA(ai, bj, At, Bt) do { __builtin_amdgcn_s_setprio(1); _Pragma("unroll") for (int m = 0; m < 4; ++m) _Pragma("unroll") for (int n = 0; n < 2; ++n) _Pragma("unroll") for (int k = 0; k < 2; ++k) \
;         acc[ai][bj][m][n] = __builtin_amdgcn_mfma_f32_16x16x32_bf16(Bt[n][k], At[m][k], acc[ai][bj][m][n], 0, 0, 0); __builtin_amdgcn_s_setprio(0); } while (0)
; #define PG8_WAIT_V(n) asm volatile("s_waitcnt vmcnt(" #n ")" ::: "memory")
; #define PG8_WAIT_L(n) asm volatile("s_waitcnt lgkmcnt(" #n ")" ::: "memory")
; #define PG8_BAR __builtin_amdgcn_s_barrier()
; #define PG8_SCHED __builtin_amdgcn_sched_barrier(0)
; template <class Epi, bool GS = false>
; __device__ __forceinline__ void gemm_phase(LAS unsigned char* lds, const Gemm g, const StaticOrder& S, const Epi& E, const int tid) {
;     ...
;             PG8_WAIT_V(8); PG8_WAIT_L(0); PG8_BAR; PG8_MMA(1, 0, At, B0); PG8_MMA(1, 1, At, B1); PG8_BAR; PG8_SCHED;
;             PG8_LDB(B0, 1, 0); PG8_LDB(B1, 1, 1); PG8_SCHED; PG8_LDA(At, 1, 0); PG8_STAGE(PG8_SA(0, 1), a2 + hstepA, voffA);
;             PG8_WAIT_V(8); PG8_WAIT_L(0); PG8_BAR; PG8_MMA(0, 0, At, B0); PG8_MMA(0, 1, At, B1); PG8_BAR; PG8_SCHED;
;             PG8_LDA(At, 1, 1); PG8_STAGE(PG8_SB(1, 0), b3, voffB); PG8_STAGE(PG8_SB(1, 1), b3 + hstepB, voffB); PG8_STAGE(PG8_SA(1, 0), a3, voffA);
;             PG8_WAIT_V(8); PG8_WAIT_L(0); PG8_BAR; PG8_MMA(1, 0, At, B0); PG8_MMA(1, 1, At, B1); PG8_BAR; PG8_SCHED;
	v_mfma_f32_16x16x32_bf16 v[62:65], v[130:133], v[180:183], v[62:65]
	v_mfma_f32_16x16x32_bf16 v[58:61], v[138:141], v[180:183], v[58:61]
	v_mfma_f32_16x16x32_bf16 v[46:49], v[130:133], v[216:219], v[46:49]
	v_mfma_f32_16x16x32_bf16 v[42:45], v[138:141], v[216:219], v[42:45]
	v_mfma_f32_16x16x32_bf16 v[30:33], v[130:133], v[224:227], v[30:33]
	v_mfma_f32_16x16x32_bf16 v[26:29], v[138:141], v[224:227], v[26:29]
	v_mfma_f32_16x16x32_bf16 v[14:17], v[130:133], v[232:235], v[14:17]
	v_mfma_f32_16x16x32_bf16 v[10:13], v[138:141], v[232:235], v[10:13]
	v_mfma_f32_16x16x32_bf16 v[62:65], v[134:137], v[184:187], v[62:65]
	v_mfma_f32_16x16x32_bf16 v[58:61], v[142:145], v[184:187], v[58:61]
	v_mfma_f32_16x16x32_bf16 v[46:49], v[134:137], v[220:223], v[46:49]
	v_mfma_f32_16x16x32_bf16 v[42:45], v[142:145], v[220:223], v[42:45]
	v_mfma_f32_16x16x32_bf16 v[30:33], v[134:137], v[228:231], v[30:33]
	v_mfma_f32_16x16x32_bf16 v[26:29], v[142:145], v[228:231], v[26:29]
	v_mfma_f32_16x16x32_bf16 v[14:17], v[134:137], v[236:239], v[14:17]
	v_mfma_f32_16x16x32_bf16 v[10:13], v[142:145], v[236:239], v[10:13]
	s_setprio 0
	s_setprio 1
	v_mfma_f32_16x16x32_bf16 v[54:57], v[146:149], v[180:183], v[54:57]
	v_mfma_f32_16x16x32_bf16 v[50:53], v[154:157], v[180:183], v[50:53]
	v_mfma_f32_16x16x32_bf16 v[38:41], v[146:149], v[216:219], v[38:41]
	v_mfma_f32_16x16x32_bf16 v[34:37], v[154:157], v[216:219], v[34:37]
	v_mfma_f32_16x16x32_bf16 v[22:25], v[146:149], v[224:227], v[22:25]
	v_mfma_f32_16x16x32_bf16 v[18:21], v[154:157], v[224:227], v[18:21]
	v_mfma_f32_16x16x32_bf16 v[6:9], v[146:149], v[232:235], v[6:9]
	v_mfma_f32_16x16x32_bf16 v[2:5], v[154:157], v[232:235], v[2:5]
	v_mfma_f32_16x16x32_bf16 v[54:57], v[150:153], v[184:187], v[54:57]
	v_mfma_f32_16x16x32_bf16 v[50:53], v[158:161], v[184:187], v[50:53]
	v_mfma_f32_16x16x32_bf16 v[38:41], v[150:153], v[220:223], v[38:41]
	v_mfma_f32_16x16x32_bf16 v[34:37], v[158:161], v[220:223], v[34:37]
	v_mfma_f32_16x16x32_bf16 v[22:25], v[150:153], v[228:231], v[22:25]
	v_mfma_f32_16x16x32_bf16 v[18:21], v[158:161], v[228:231], v[18:21]
	v_mfma_f32_16x16x32_bf16 v[6:9], v[150:153], v[236:239], v[6:9]
	v_mfma_f32_16x16x32_bf16 v[2:5], v[158:161], v[236:239], v[2:5]
	s_setprio 0
.Ltail9_skip1:
	s_setprio 0
	s_barrier
	s_add_i32 s53, 0, 0x18000
	v_add_u32_e32 v0, s53, v190
	s_add_i32 s54, 0, 0x1c000
	ds_read_b128 v[130:133], v0
	ds_read_b128 v[134:137], v0 offset:1024
	ds_read_b128 v[138:141], v0 offset:2048
	ds_read_b128 v[142:145], v0 offset:3072
	v_add_u32_e32 v0, s54, v190
	ds_read_b128 v[146:149], v0
	ds_read_b128 v[150:153], v0 offset:1024
	ds_read_b128 v[154:157], v0 offset:2048
	ds_read_b128 v[158:161], v0 offset:3072
	s_add_u32 s20, s34, 0xb0000
	s_addc_u32 s21, s35, 0
	s_mov_b32 m0, s38
	v_lshl_add_u64 v[244:245], s[20:21], 0, v[164:165]
	ds_read_b128 v[180:183], v192 offset:32768
	ds_read_b128 v[184:187], v192 offset:33792
	ds_read_b128 v[216:219], v192 offset:34816
	ds_read_b128 v[220:223], v192 offset:35840
	ds_read_b128 v[224:227], v192 offset:36864
	ds_read_b128 v[228:231], v192 offset:37888
	ds_read_b128 v[232:235], v192 offset:38912
	ds_read_b128 v[236:239], v192 offset:39936
	global_load_lds_dwordx4 v[244:245], off
	v_lshl_add_u64 v[244:245], s[20:21], 0, v[162:163]
	s_mov_b32 m0, s39
	s_nop 0
	global_load_lds_dwordx4 v[244:245], off
	s_waitcnt vmcnt(8)
	s_waitcnt lgkmcnt(0)
	s_barrier
	s_setprio 1
	s_waitcnt lgkmcnt(0)
	s_cmp_eq_u32 s100, 2
	s_cbranch_scc1 .Ltail9_skip2
	v_mfma_f32_16x16x32_bf16 v[126:129], v[130:133], v[180:183], v[126:129]
	v_mfma_f32_16x16x32_bf16 v[122:125], v[138:141], v[180:183], v[122:125]
	v_mfma_f32_16x16x32_bf16 v[110:113], v[130:133], v[216:219], v[110:113]
	v_mfma_f32_16x16x32_bf16 v[106:109], v[138:141], v[216:219], v[106:109]
	v_mfma_f32_16x16x32_bf16 v[94:97], v[130:133], v[224:227], v[94:97]
	v_mfma_f32_16x16x32_bf16 v[90:93], v[138:141], v[224:227], v[90:93]
	v_mfma_f32_16x16x32_bf16 v[78:81], v[130:133], v[232:235], v[78:81]
	v_mfma_f32_16x16x32_bf16 v[74:77], v[138:141], v[232:235], v[74:77]
	v_mfma_f32_16x16x32_bf16 v[126:129], v[134:137], v[184:187], v[126:129]
	v_mfma_f32_16x16x32_bf16 v[122:125], v[142:145], v[184:187], v[122:125]
	v_mfma_f32_16x16x32_bf16 v[110:113], v[134:137], v[220:223], v[110:113]
	v_mfma_f32_16x16x32_bf16 v[106:109], v[142:145], v[220:223], v[106:109]
	v_mfma_f32_16x16x32_bf16 v[94:97], v[134:137], v[228:231], v[94:97]
	v_mfma_f32_16x16x32_bf16 v[90:93], v[142:145], v[228:231], v[90:93]
	v_mfma_f32_16x16x32_bf16 v[78:81], v[134:137], v[236:239], v[78:81]
	v_mfma_f32_16x16x32_bf16 v[74:77], v[142:145], v[236:239], v[74:77]
	s_setprio 0
	s_setprio 1
	v_mfma_f32_16x16x32_bf16 v[118:121], v[146:149], v[180:183], v[118:121]
	v_mfma_f32_16x16x32_bf16 v[114:117], v[154:157], v[180:183], v[114:117]
	v_mfma_f32_16x16x32_bf16 v[102:105], v[146:149], v[216:219], v[102:105]
	v_mfma_f32_16x16x32_bf16 v[98:101], v[154:157], v[216:219], v[98:101]
	v_mfma_f32_16x16x32_bf16 v[86:89], v[146:149], v[224:227], v[86:89]
	v_mfma_f32_16x16x32_bf16 v[82:85], v[154:157], v[224:227], v[82:85]
	v_mfma_f32_16x16x32_bf16 v[70:73], v[146:149], v[232:235], v[70:73]
	v_mfma_f32_16x16x32_bf16 v[66:69], v[154:157], v[232:235], v[66:69]
	v_mfma_f32_16x16x32_bf16 v[118:121], v[150:153], v[184:187], v[118:121]
	v_mfma_f32_16x16x32_bf16 v[114:117], v[158:161], v[184:187], v[114:117]
	v_mfma_f32_16x16x32_bf16 v[102:105], v[150:153], v[220:223], v[102:105]
	v_mfma_f32_16x16x32_bf16 v[98:101], v[158:161], v[220:223], v[98:101]
	v_mfma_f32_16x16x32_bf16 v[86:89], v[150:153], v[228:231], v[86:89]
	v_mfma_f32_16x16x32_bf16 v[82:85], v[158:161], v[228:231], v[82:85]
	v_mfma_f32_16x16x32_bf16 v[70:73], v[150:153], v[236:239], v[70:73]
	v_mfma_f32_16x16x32_bf16 v[66:69], v[158:161], v[236:239], v[66:69]
	s_setprio 0
; #define PG8_STAGE(bufoff, gbase, voff) do { _Pragma("unroll") for (int _i = 0; _i < 2; ++_i) \
;         __builtin_amdgcn_global_load_lds((const unsigned*)((const char*)(gbase) + (voff)[_i]), (LAS unsigned*)(lds + (bufoff) + ldsw + _i * 8192), 16, 0, 0); } while (0)
; #define PG8_LDA(dst, b, h) do { _Pragma("unroll") for (int m = 0; m < 4; ++m) _Pragma("unroll") for (int k = 0; k < 2; ++k) dst[m][k] = *(const LAS bf16x8*)(lds + PG8_SA(b, h) + aoff + m * 2048 + k * 1024); } while (0)
; #define PG8_WAIT_V(n) asm volatile("s_waitcnt vmcnt(" #n ")" ::: "memory")
; template <class Epi, bool GS = false>
; __device__ __forceinline__ void gemm_phase(LAS unsigned char* lds, const Gemm g, const StaticOrder& S, const Epi& E, const int tid) {
;     ...
;             PG8_WAIT_V(8); PG8_WAIT_L(0); PG8_BAR; PG8_MMA(0, 0, At, B0); PG8_MMA(0, 1, At, B1); PG8_BAR; PG8_SCHED;
;             PG8_LDA(At, 1, 1); PG8_STAGE(PG8_SB(1, 0), b3, voffB); PG8_STAGE(PG8_SB(1, 1), b3 + hstepB, voffB); PG8_STAGE(PG8_SA(1, 0), a3, voffA);
;             PG8_WAIT_V(8); PG8_WAIT_L(0); PG8_BAR; PG8_MMA(1, 0, At, B0); PG8_MMA(1, 1, At, B1); PG8_BAR; PG8_SCHED;
;         }
;     __device__ __forceinline__ void operator()(const f32x4 (&acc)[2][2][4][2], const Unit& u, int wr, int wc, int fr, int fq) const {
;         const int col0 = u.pn * BM + wc * 32 + 4 * fq;
; #pragma unroll
;         for (int ai = 0; ai < 2; ++ai) {
;             const int grb = row_base + u.pm * BM + ai * HALF + wr * 64;
;             const int seq = grb < MP ? (grb >> 11) : NPB + ((grb - MP) >> 6);
;             const float* gp = gate + (size_t)seq * (6 * DM) + col0;
;             f32x4 gv[2][2];
; #pragma unroll
;             for (int bj = 0; bj < 2; ++bj)
; #pragma unroll
;                 for (int n = 0; n < 2; ++n) gv[bj][n] = *(const f32x4*)(gp + bj * HALF + n * 16);
;             if (u.part == 0) {
; #pragma unroll
;                 for (int mp = 0; mp < 2; ++mp) {
;                 f32x4 xv[2][2][2];
; #pragma unroll
;                 for (int mm = 0; mm < 2; ++mm) { const int gr = grb + (2 * mp + mm) * 16 + fr;
;                     const float* xr = (gr < MP ? xin_p + (size_t)gr * DM : xin_s + (size_t)(gr - MP) * DM) + col0;
; #pragma unroll
;                     for (int bj = 0; bj < 2; ++bj)
; #pragma unroll
;                         for (int n = 0; n < 2; ++n) xv[mm][bj][n] = *(const f32x4*)(xr + bj * HALF + n * 16); }
.Ltail9_skip2:
	s_setprio 0
	s_barrier
	s_add_i32 s20, s53, s10
	v_lshl_add_u64 v[188:189], v[188:189], 0, s[0:1]
	s_mov_b32 m0, s20
	ds_read_b128 v[180:183], v192 offset:49152
	ds_read_b128 v[184:187], v192 offset:50176
	ds_read_b128 v[216:219], v192 offset:51200
	ds_read_b128 v[220:223], v192 offset:52224
	ds_read_b128 v[224:227], v192 offset:53248
	ds_read_b128 v[228:231], v192 offset:54272
	ds_read_b128 v[232:235], v192 offset:55296
	ds_read_b128 v[236:239], v192 offset:56320
	global_load_lds_dwordx4 v[188:189], off
	s_add_i32 m0, s20, 0x2000
	s_add_u32 s20, s30, 0xb0080
	v_lshl_add_u64 v[188:189], v[194:195], 0, s[0:1]
	s_addc_u32 s21, s31, 0
	s_add_i32 s30, s54, s10
	global_load_lds_dwordx4 v[188:189], off
	v_lshl_add_u64 v[188:189], s[20:21], 0, v[164:165]
	s_mov_b32 m0, s30
	s_nop 0
	global_load_lds_dwordx4 v[188:189], off
	v_lshl_add_u64 v[188:189], s[20:21], 0, v[162:163]
	s_add_i32 m0, s30, 0x2000
	s_nop 0
	global_load_lds_dwordx4 v[188:189], off
	v_lshl_add_u64 v[188:189], v[240:241], 0, s[0:1]
	s_mov_b32 m0, s43
	s_nop 0
	global_load_lds_dwordx4 v[188:189], off
	v_lshl_add_u64 v[188:189], v[242:243], 0, s[0:1]
	s_mov_b32 m0, s44
	s_nop 0
	global_load_lds_dwordx4 v[188:189], off
	s_waitcnt vmcnt(8)
	s_waitcnt lgkmcnt(0)
	s_barrier
	s_setprio 1
	s_waitcnt lgkmcnt(0)
	s_cmp_eq_u32 s100, 1
	s_cbranch_scc1 .Ltail9_skip3
	v_mfma_f32_16x16x32_bf16 v[62:65], v[130:133], v[180:183], v[62:65]
	v_mfma_f32_16x16x32_bf16 v[58:61], v[138:141], v[180:183], v[58:61]
	v_mfma_f32_16x16x32_bf16 v[46:49], v[130:133], v[216:219], v[46:49]
	v_mfma_f32_16x16x32_bf16 v[42:45], v[138:141], v[216:219], v[42:45]
	v_mfma_f32_16x16x32_bf16 v[30:33], v[130:133], v[224:227], v[30:33]
	v_mfma_f32_16x16x32_bf16 v[26:29], v[138:141], v[224:227], v[26:29]
	v_mfma_f32_16x16x32_bf16 v[14:17], v[130:133], v[232:235], v[14:17]
	v_mfma_f32_16x16x32_bf16 v[10:13], v[138:141], v[232:235], v[10:13]
	v_mfma_f32_16x16x32_bf16 v[62:65], v[134:137], v[184:187], v[62:65]
	v_mfma_f32_16x16x32_bf16 v[58:61], v[142:145], v[184:187], v[58:61]
	v_mfma_f32_16x16x32_bf16 v[46:49], v[134:137], v[220:223], v[46:49]
	v_mfma_f32_16x16x32_bf16 v[42:45], v[142:145], v[220:223], v[42:45]
	v_mfma_f32_16x16x32_bf16 v[30:33], v[134:137], v[228:231], v[30:33]
	v_mfma_f32_16x16x32_bf16 v[26:29], v[142:145], v[228:231], v[26:29]
	v_mfma_f32_16x16x32_bf16 v[14:17], v[134:137], v[236:239], v[14:17]
	v_mfma_f32_16x16x32_bf16 v[10:13], v[142:145], v[236:239], v[10:13]
	s_setprio 0
	s_setprio 1
	v_mfma_f32_16x16x32_bf16 v[54:57], v[146:149], v[180:183], v[54:57]
	v_mfma_f32_16x16x32_bf16 v[50:53], v[154:157], v[180:183], v[50:53]
	v_mfma_f32_16x16x32_bf16 v[38:41], v[146:149], v[216:219], v[38:41]
	v_mfma_f32_16x16x32_bf16 v[34:37], v[154:157], v[216:219], v[34:37]
	v_mfma_f32_16x16x32_bf16 v[22:25], v[146:149], v[224:227], v[22:25]
	v_mfma_f32_16x16x32_bf16 v[18:21], v[154:157], v[224:227], v[18:21]
	v_mfma_f32_16x16x32_bf16 v[6:9], v[146:149], v[232:235], v[6:9]
	v_mfma_f32_16x16x32_bf16 v[2:5], v[154:157], v[232:235], v[2:5]
	v_mfma_f32_16x16x32_bf16 v[54:57], v[150:153], v[184:187], v[54:57]
	v_mfma_f32_16x16x32_bf16 v[50:53], v[158:161], v[184:187], v[50:53]
	v_mfma_f32_16x16x32_bf16 v[38:41], v[150:153], v[220:223], v[38:41]
	v_mfma_f32_16x16x32_bf16 v[34:37], v[158:161], v[220:223], v[34:37]
	v_mfma_f32_16x16x32_bf16 v[22:25], v[150:153], v[228:231], v[22:25]
	v_mfma_f32_16x16x32_bf16 v[18:21], v[158:161], v[228:231], v[18:21]
	v_mfma_f32_16x16x32_bf16 v[6:9], v[150:153], v[236:239], v[6:9]
	v_mfma_f32_16x16x32_bf16 v[2:5], v[158:161], v[236:239], v[2:5]
	s_setprio 0
.Ltail9_skip3:
	s_setprio 0
	s_barrier
	s_add_i32 s52, s52, 2
	s_add_u32 s50, s50, 0x100
	s_addc_u32 s51, s51, 0
	s_cmp_gt_u32 s52, 41
	s_mov_b64 s[20:21], s[22:23]
	s_cbranch_scc0 .LBB0_993
	s_and_b64 vcc, exec, s[14:15]
	s_cbranch_vccz .LBB0_996
	s_barrier
.LBB0_996:
	s_lshl_b32 s22, s48, 8
	s_add_i32 s22, s22, s42
	s_add_i32 s21, s22, 0xffff8000
	s_lshr_b32 s21, s21, 6
	s_ashr_i32 s20, s22, 11
	s_add_i32 s21, s21, 16
	s_cmp_lt_i32 s22, 0x8000
	s_cselect_b32 s20, s20, s21
	v_lshl_or_b32 v130, s49, 8, v191
	s_mul_hi_i32 s21, s20, 0x6000
	s_mulk_i32 s20, 0x6000
	v_ashrrev_i32_e32 v131, 31, v130
	s_add_u32 s20, s40, s20
	s_addc_u32 s21, s41, s21
	v_lshlrev_b64 v[180:181], 2, v[130:131]
	v_lshl_add_u64 v[130:131], s[20:21], 0, v[180:181]
	v_or_b32_e32 v182, s22, v169
	s_mov_b32 s20, 0x8000
	v_readlane_b32 s34, v255, 0
	v_add_u32_e32 v0, 0xffff8000, v182
	v_cmp_gt_i32_e32 vcc, s20, v182
	v_readlane_b32 s35, v255, 1
	v_ashrrev_i32_e32 v183, 31, v182
	v_cndmask_b32_e32 v146, v0, v182, vcc
	v_mov_b32_e32 v0, s35
	v_mov_b32_e32 v148, s25
	v_cndmask_b32_e32 v147, 0, v183, vcc
	v_cndmask_b32_e32 v149, v0, v148, vcc
	v_mov_b32_e32 v0, s34
	v_mov_b32_e32 v148, s24
	v_cndmask_b32_e32 v148, v0, v148, vcc
	v_lshlrev_b64 v[146:147], 12, v[146:147]
	v_lshl_add_u64 v[146:147], v[148:149], 0, v[146:147]
	v_lshl_add_u64 v[146:147], v[146:147], 0, v[180:181]
	global_load_dwordx4 v[142:145], v[130:131], off
	global_load_dwordx4 v[138:141], v[130:131], off offset:64
	global_load_dwordx4 v[134:137], v[130:131], off offset:512
	s_nop 0
	global_load_dwordx4 v[130:133], v[130:131], off offset:576
	s_nop 0
	global_load_dwordx4 v[158:161], v[146:147], off
	global_load_dwordx4 v[154:157], v[146:147], off offset:64
	global_load_dwordx4 v[150:153], v[146:147], off offset:512
	s_nop 0
	global_load_dwordx4 v[146:149], v[146:147], off offset:576
	v_or_b32_e32 v186, 16, v182
	s_movk_i32 s20, 0x7fff
	v_cmp_lt_i32_e32 vcc, s20, v186
	s_and_saveexec_b64 s[20:21], vcc
	s_xor_b64 s[20:21], exec, s[20:21]
	v_add_u32_e32 v0, 0xffff8010, v182
	v_lshlrev_b64 v[184:185], 12, v[0:1]
	v_mov_b32_e32 v187, v1
	v_lshl_add_u64 v[188:189], s[34:35], 0, v[184:185]
	v_lshlrev_b64 v[184:185], 12, v[186:187]
	s_andn2_saveexec_b64 s[20:21], s[20:21]
	v_ashrrev_i32_e32 v187, 31, v186
	v_lshlrev_b64 v[184:185], 12, v[186:187]
	v_lshl_add_u64 v[188:189], s[24:25], 0, v[184:185]
	s_or_b64 exec, exec, s[20:21]
	v_lshl_add_u64 v[194:195], v[188:189], 0, v[180:181]
	global_load_dwordx4 v[186:189], v[194:195], off
	global_load_dwordx4 v[216:219], v[194:195], off offset:64
	global_load_dwordx4 v[220:223], v[194:195], off offset:512
	global_load_dwordx4 v[224:227], v[194:195], off offset:576
	v_lshlrev_b64 v[194:195], 12, v[182:183]
	s_waitcnt vmcnt(0)
;     __device__ __forceinline__ void operator()(const f32x4 (&acc)[2][2][4][2], const Unit& u, int wr, int wc, int fr, int fq) const {
;     ...
;                 for (int mp = 0; mp < 2; ++mp) {
;                 f32x4 xv[2][2][2];
; #pragma unroll
;                 for (int mm = 0; mm < 2; ++mm) { const int gr = grb + (2 * mp + mm) * 16 + fr;
;                     const float* xr = (gr < MP ? xin_p + (size_t)gr * DM : xin_s + (size_t)(gr - MP) * DM) + col0;
; #pragma unroll
;                     for (int bj = 0; bj < 2; ++bj)
; #pragma unroll
;                         for (int n = 0; n < 2; ++n) xv[mm][bj][n] = *(const f32x4*)(xr + bj * HALF + n * 16); }
; #pragma unroll
;                 for (int mm = 0; mm < 2; ++mm) { const int m = 2 * mp + mm; const int gr = grb + m * 16 + fr; float* orow = out + (size_t)gr * DM + col0;
; #pragma unroll
;                     for (int bj = 0; bj < 2; ++bj)
; #pragma unroll
;                         for (int n = 0; n < 2; ++n) *(f32x4*)(orow + bj * HALF + n * 16) = xv[mm][bj][n] + gv[bj][n] * acc[ai][bj][m][n]; }
	v_pk_fma_f32 v[146:147], v[114:115], v[130:131], v[146:147]
	v_or_b32_e32 v114, 32, v182
	s_mov_b32 s20, 0x8000
	v_pk_fma_f32 v[118:119], v[118:119], v[134:135], v[150:151]
	v_add_u32_e32 v0, 0xffff8020, v182
	v_lshl_add_u64 v[150:151], s[24:25], 0, v[194:195]
	v_ashrrev_i32_e32 v115, 31, v114
	v_cmp_gt_i32_e32 vcc, s20, v114
	v_pk_fma_f32 v[128:129], v[128:129], v[144:145], v[160:161]
	v_pk_fma_f32 v[126:127], v[126:127], v[142:143], v[158:159]
	v_pk_fma_f32 v[124:125], v[124:125], v[140:141], v[156:157]
	v_pk_fma_f32 v[122:123], v[122:123], v[138:139], v[154:155]
	v_pk_fma_f32 v[120:121], v[120:121], v[136:137], v[152:153]
	v_mov_b32_e32 v154, s35
	v_mov_b32_e32 v155, s25
	v_mov_b32_e32 v156, s34
	v_mov_b32_e32 v157, s24
	v_lshl_add_u64 v[150:151], v[150:151], 0, v[180:181]
	v_cndmask_b32_e32 v153, 0, v115, vcc
	v_cndmask_b32_e32 v152, v0, v114, vcc
	v_pk_fma_f32 v[148:149], v[116:117], v[132:133], v[148:149]
	v_lshl_add_u64 v[116:117], s[24:25], 0, v[184:185]
	v_cndmask_b32_e32 v155, v154, v155, vcc
	v_cndmask_b32_e32 v154, v156, v157, vcc
	s_cmp_eq_u32 s100, 2
	s_cselect_b32 m0, 0, -1
	s_cselect_b64 exec, 0, -1
	global_store_dwordx4 v[150:151], v[126:129], off
	global_store_dwordx4 v[150:151], v[122:125], off offset:64
	global_store_dwordx4 v[150:151], v[118:121], off offset:512
	global_store_dwordx4 v[150:151], v[146:149], off offset:576
	s_mov_b64 exec, -1
	v_lshl_add_u64 v[116:117], v[116:117], 0, v[180:181]
	v_lshlrev_b64 v[118:119], 12, v[152:153]
	v_lshl_add_u64 v[118:119], v[154:155], 0, v[118:119]
	v_lshl_add_u64 v[118:119], v[118:119], 0, v[180:181]
	s_movk_i32 s20, 0x7fff
	v_pk_fma_f32 v[112:113], v[112:113], v[144:145], v[188:189]
	v_pk_fma_f32 v[110:111], v[110:111], v[142:143], v[186:187]
	v_pk_fma_f32 v[108:109], v[108:109], v[140:141], v[218:219]
	v_pk_fma_f32 v[106:107], v[106:107], v[138:139], v[216:217]
	v_pk_fma_f32 v[104:105], v[104:105], v[136:137], v[222:223]
	v_pk_fma_f32 v[102:103], v[102:103], v[134:135], v[220:221]
	v_pk_fma_f32 v[100:101], v[100:101], v[132:133], v[226:227]
	v_pk_fma_f32 v[98:99], v[98:99], v[130:131], v[224:225]
	s_cmp_eq_u32 s100, 2
	s_cselect_b64 exec, 0, -1
	global_store_dwordx4 v[116:117], v[110:113], off
	global_store_dwordx4 v[116:117], v[106:109], off offset:64
	global_store_dwordx4 v[116:117], v[102:105], off offset:512
	global_store_dwordx4 v[116:117], v[98:101], off offset:576
	s_mov_b64 exec, -1
	global_load_dwordx4 v[110:113], v[118:119], off
	s_nop 0
	global_load_dwordx4 v[106:109], v[118:119], off offset:64
	global_load_dwordx4 v[102:105], v[118:119], off offset:512
	global_load_dwordx4 v[98:101], v[118:119], off offset:576
	v_or_b32_e32 v118, 48, v182
	v_cmp_lt_i32_e32 vcc, s20, v118
	s_and_saveexec_b64 s[20:21], vcc
	s_xor_b64 s[20:21], exec, s[20:21]
	v_add_u32_e32 v0, 0xffff8030, v182
	v_lshlrev_b64 v[116:117], 12, v[0:1]
	v_mov_b32_e32 v119, v1
	v_lshl_add_u64 v[120:121], s[34:35], 0, v[116:117]
	v_lshlrev_b64 v[116:117], 12, v[118:119]
	s_andn2_saveexec_b64 s[20:21], s[20:21]
	v_ashrrev_i32_e32 v119, 31, v118
	v_lshlrev_b64 v[116:117], 12, v[118:119]
	v_lshl_add_u64 v[120:121], s[24:25], 0, v[116:117]
	s_or_b64 exec, exec, s[20:21]
	v_lshl_add_u64 v[146:147], v[120:121], 0, v[180:181]
	global_load_dwordx4 v[118:121], v[146:147], off
	global_load_dwordx4 v[122:125], v[146:147], off offset:64
	global_load_dwordx4 v[126:129], v[146:147], off offset:512
	s_nop 0
	global_load_dwordx4 v[146:149], v[146:147], off offset:576
	s_add_i32 s20, s22, 0x80
	s_addk_i32 s22, 0x8080
	s_lshr_b32 s22, s22, 6
	v_lshlrev_b64 v[114:115], 12, v[114:115]
	s_waitcnt vmcnt(4)
	v_pk_fma_f32 v[82:83], v[82:83], v[130:131], v[98:99]
	v_lshl_add_u64 v[98:99], s[24:25], 0, v[116:117]
	s_ashr_i32 s21, s20, 11
	s_add_i32 s22, s22, 16
	v_pk_fma_f32 v[86:87], v[86:87], v[134:135], v[102:103]
	v_pk_fma_f32 v[84:85], v[84:85], v[132:133], v[100:101]
	v_lshl_add_u64 v[100:101], s[24:25], 0, v[114:115]
	v_lshl_add_u64 v[102:103], v[98:99], 0, v[180:181]
	v_or_b32_e32 v98, s20, v169
	s_cmp_lt_i32 s20, 0x8000
	s_mov_b32 s20, 0x8000
	v_pk_fma_f32 v[96:97], v[96:97], v[144:145], v[112:113]
	v_pk_fma_f32 v[94:95], v[94:95], v[142:143], v[110:111]
	v_pk_fma_f32 v[90:91], v[90:91], v[138:139], v[106:107]
	v_lshl_add_u64 v[100:101], v[100:101], 0, v[180:181]
	v_ashrrev_i32_e32 v99, 31, v98
	v_add_u32_e32 v107, 0xffff8000, v98
	v_cmp_gt_i32_e32 vcc, s20, v98
	s_cselect_b32 s20, s21, s22
	v_pk_fma_f32 v[92:93], v[92:93], v[140:141], v[108:109]
	v_pk_fma_f32 v[88:89], v[88:89], v[136:137], v[104:105]
	v_mov_b32_e32 v0, s35
	v_mov_b32_e32 v104, s25
	v_mov_b32_e32 v105, s34
	v_mov_b32_e32 v106, s24
	s_cmp_eq_u32 s100, 2
	s_cselect_b64 exec, 0, -1
	global_store_dwordx4 v[100:101], v[94:97], off
	global_store_dwordx4 v[100:101], v[90:93], off offset:64
	global_store_dwordx4 v[100:101], v[86:89], off offset:512
	global_store_dwordx4 v[100:101], v[82:85], off offset:576
	s_mov_b64 exec, -1
	s_mul_hi_i32 s21, s20, 0x6000
	s_mulk_i32 s20, 0x6000
	v_cndmask_b32_e32 v83, 0, v99, vcc
	v_cndmask_b32_e32 v82, v107, v98, vcc
	v_cndmask_b32_e32 v85, v0, v104, vcc
	v_cndmask_b32_e32 v84, v105, v106, vcc
	v_lshlrev_b64 v[82:83], 12, v[82:83]
	s_add_u32 s20, s40, s20
	v_lshl_add_u64 v[82:83], v[84:85], 0, v[82:83]
	s_addc_u32 s21, s41, s21
	v_lshl_add_u64 v[82:83], v[82:83], 0, v[180:181]
	v_lshl_add_u64 v[84:85], s[20:21], 0, v[180:181]
	s_movk_i32 s20, 0x7fff
	s_waitcnt vmcnt(7)
	v_pk_fma_f32 v[80:81], v[80:81], v[144:145], v[120:121]
	v_pk_fma_f32 v[78:79], v[78:79], v[142:143], v[118:119]
	s_waitcnt vmcnt(6)
	v_pk_fma_f32 v[76:77], v[76:77], v[140:141], v[124:125]
	v_pk_fma_f32 v[74:75], v[74:75], v[138:139], v[122:123]
	s_waitcnt vmcnt(5)
; #define PG8_BAR __builtin_amdgcn_s_barrier()
; template <class Epi, bool GS = false>
; __device__ __forceinline__ void gemm_phase(LAS unsigned char* lds, const Gemm g, const StaticOrder& S, const Epi& E, const int tid) {
;     ...
;         if (!has_next) break;
; #pragma unroll
;         for (int a = 0; a < 2; ++a)
; #pragma unroll
;             for (int b = 0; b < 2; ++b)
; #pragma unroll
;                 for (int m = 0; m < 4; ++m)
; #pragma unroll
;                     for (int n = 0; n < 2; ++n) acc[a][b][m][n] = (f32x4){0.f, 0.f, 0.f, 0.f};
;         cur = nxt; cA = nA; cB = nB; ++ui;
;         if (wr == 1) PG8_BAR;
;     __device__ __forceinline__ void operator()(const f32x4 (&acc)[2][2][4][2], const Unit& u, int wr, int wc, int fr, int fq) const {
;     ...
;                 for (int mm = 0; mm < 2; ++mm) { const int gr = grb + (2 * mp + mm) * 16 + fr;
;                     const float* xr = (gr < MP ? xin_p + (size_t)gr * DM : xin_s + (size_t)(gr - MP) * DM) + col0;
; #pragma unroll
;                     for (int bj = 0; bj < 2; ++bj)
; #pragma unroll
;                         for (int n = 0; n < 2; ++n) xv[mm][bj][n] = *(const f32x4*)(xr + bj * HALF + n * 16); }
; #pragma unroll
;                 for (int mm = 0; mm < 2; ++mm) { const int m = 2 * mp + mm; const int gr = grb + m * 16 + fr; float* orow = out + (size_t)gr * DM + col0;
; #pragma unroll
;                     for (int bj = 0; bj < 2; ++bj)
; #pragma unroll
;                         for (int n = 0; n < 2; ++n) *(f32x4*)(orow + bj * HALF + n * 16) = xv[mm][bj][n] + gv[bj][n] * acc[ai][bj][m][n]; }
	v_pk_fma_f32 v[72:73], v[72:73], v[136:137], v[128:129]
	v_pk_fma_f32 v[70:71], v[70:71], v[134:135], v[126:127]
	s_waitcnt vmcnt(4)
	v_pk_fma_f32 v[68:69], v[68:69], v[132:133], v[148:149]
	v_pk_fma_f32 v[66:67], v[66:67], v[130:131], v[146:147]
	s_cmp_eq_u32 s100, 2
	s_cselect_b64 exec, 0, -1
	global_store_dwordx4 v[102:103], v[78:81], off
	global_store_dwordx4 v[102:103], v[74:77], off offset:64
	global_store_dwordx4 v[102:103], v[70:73], off offset:512
	global_store_dwordx4 v[102:103], v[66:69], off offset:576
	s_mov_b64 exec, -1
	global_load_dwordx4 v[78:81], v[84:85], off
	s_nop 0
	global_load_dwordx4 v[74:77], v[84:85], off offset:64
	global_load_dwordx4 v[70:73], v[84:85], off offset:512
	global_load_dwordx4 v[66:69], v[84:85], off offset:576
	global_load_dwordx4 v[94:97], v[82:83], off
	global_load_dwordx4 v[90:93], v[82:83], off offset:64
	global_load_dwordx4 v[86:89], v[82:83], off offset:512
	s_nop 0
	global_load_dwordx4 v[82:85], v[82:83], off offset:576
	v_or_b32_e32 v102, 16, v98
	v_cmp_lt_i32_e32 vcc, s20, v102
	s_and_saveexec_b64 s[20:21], vcc
	s_xor_b64 s[20:21], exec, s[20:21]
	v_add_u32_e32 v0, 0xffff8010, v98
	v_lshlrev_b64 v[100:101], 12, v[0:1]
	v_mov_b32_e32 v103, v1
	v_lshl_add_u64 v[104:105], s[34:35], 0, v[100:101]
	v_lshlrev_b64 v[100:101], 12, v[102:103]
	s_andn2_saveexec_b64 s[20:21], s[20:21]
	v_ashrrev_i32_e32 v103, 31, v102
	v_lshlrev_b64 v[100:101], 12, v[102:103]
	v_lshl_add_u64 v[104:105], s[24:25], 0, v[100:101]
	s_or_b64 exec, exec, s[20:21]
	v_lshl_add_u64 v[114:115], v[104:105], 0, v[180:181]
	global_load_dwordx4 v[102:105], v[114:115], off
	global_load_dwordx4 v[106:109], v[114:115], off offset:64
	global_load_dwordx4 v[110:113], v[114:115], off offset:512
	s_nop 0
	global_load_dwordx4 v[114:117], v[114:115], off offset:576
	v_lshlrev_b64 v[118:119], 12, v[98:99]
	s_waitcnt vmcnt(4)
	v_pk_fma_f32 v[82:83], v[50:51], v[66:67], v[82:83]
	v_or_b32_e32 v50, 32, v98
	s_mov_b32 s20, 0x8000
	v_pk_fma_f32 v[54:55], v[54:55], v[70:71], v[86:87]
	v_add_u32_e32 v0, 0xffff8020, v98
	v_lshl_add_u64 v[86:87], s[24:25], 0, v[118:119]
	v_ashrrev_i32_e32 v51, 31, v50
	v_cmp_gt_i32_e32 vcc, s20, v50
	v_pk_fma_f32 v[64:65], v[64:65], v[80:81], v[96:97]
	v_pk_fma_f32 v[62:63], v[62:63], v[78:79], v[94:95]
	v_pk_fma_f32 v[60:61], v[60:61], v[76:77], v[92:93]
	v_pk_fma_f32 v[58:59], v[58:59], v[74:75], v[90:91]
	v_pk_fma_f32 v[56:57], v[56:57], v[72:73], v[88:89]
	v_mov_b32_e32 v90, s35
	v_mov_b32_e32 v91, s25
	v_mov_b32_e32 v92, s34
	v_mov_b32_e32 v93, s24
	v_lshl_add_u64 v[86:87], v[86:87], 0, v[180:181]
	v_cndmask_b32_e32 v89, 0, v51, vcc
	v_cndmask_b32_e32 v88, v0, v50, vcc
	v_pk_fma_f32 v[84:85], v[52:53], v[68:69], v[84:85]
	v_lshl_add_u64 v[52:53], s[24:25], 0, v[100:101]
	v_cndmask_b32_e32 v91, v90, v91, vcc
	v_cndmask_b32_e32 v90, v92, v93, vcc
	s_cmp_eq_u32 s100, 1
	s_cselect_b64 exec, 0, -1
	global_store_dwordx4 v[86:87], v[62:65], off
	global_store_dwordx4 v[86:87], v[58:61], off offset:64
	global_store_dwordx4 v[86:87], v[54:57], off offset:512
	global_store_dwordx4 v[86:87], v[82:85], off offset:576
	s_mov_b64 exec, -1
	v_lshl_add_u64 v[52:53], v[52:53], 0, v[180:181]
	v_lshlrev_b64 v[54:55], 12, v[88:89]
	v_lshl_add_u64 v[54:55], v[90:91], 0, v[54:55]
	v_lshl_add_u64 v[54:55], v[54:55], 0, v[180:181]
	s_movk_i32 s20, 0x7fff
	s_waitcnt vmcnt(7)
	v_pk_fma_f32 v[48:49], v[48:49], v[80:81], v[104:105]
	v_pk_fma_f32 v[46:47], v[46:47], v[78:79], v[102:103]
	s_waitcnt vmcnt(6)
	v_pk_fma_f32 v[44:45], v[44:45], v[76:77], v[108:109]
	v_pk_fma_f32 v[42:43], v[42:43], v[74:75], v[106:107]
	s_waitcnt vmcnt(5)
	v_pk_fma_f32 v[40:41], v[40:41], v[72:73], v[112:113]
	v_pk_fma_f32 v[38:39], v[38:39], v[70:71], v[110:111]
	s_waitcnt vmcnt(4)
	v_pk_fma_f32 v[36:37], v[36:37], v[68:69], v[116:117]
	v_pk_fma_f32 v[34:35], v[34:35], v[66:67], v[114:115]
	s_cmp_eq_u32 s100, 1
	s_cselect_b64 exec, 0, -1
	global_store_dwordx4 v[52:53], v[46:49], off
	global_store_dwordx4 v[52:53], v[42:45], off offset:64
	global_store_dwordx4 v[52:53], v[38:41], off offset:512
	global_store_dwordx4 v[52:53], v[34:37], off offset:576
	s_mov_b64 exec, -1
	global_load_dwordx4 v[46:49], v[54:55], off
	s_nop 0
	global_load_dwordx4 v[42:45], v[54:55], off offset:64
	global_load_dwordx4 v[38:41], v[54:55], off offset:512
	global_load_dwordx4 v[34:37], v[54:55], off offset:576
	v_or_b32_e32 v54, 48, v98
	v_cmp_lt_i32_e32 vcc, s20, v54
	s_and_saveexec_b64 s[20:21], vcc
	s_xor_b64 s[20:21], exec, s[20:21]
	v_add_u32_e32 v0, 0xffff8030, v98
	v_lshlrev_b64 v[52:53], 12, v[0:1]
	v_mov_b32_e32 v55, v1
	v_lshl_add_u64 v[56:57], s[34:35], 0, v[52:53]
	v_lshlrev_b64 v[52:53], 12, v[54:55]
	s_andn2_saveexec_b64 s[20:21], s[20:21]
	v_ashrrev_i32_e32 v55, 31, v54
	v_lshlrev_b64 v[52:53], 12, v[54:55]
	v_lshl_add_u64 v[56:57], s[24:25], 0, v[52:53]
	s_or_b64 exec, exec, s[20:21]
	v_lshl_add_u64 v[82:83], v[56:57], 0, v[180:181]
	global_load_dwordx4 v[54:57], v[82:83], off
	global_load_dwordx4 v[58:61], v[82:83], off offset:64
	global_load_dwordx4 v[62:65], v[82:83], off offset:512
	s_nop 0
	global_load_dwordx4 v[82:85], v[82:83], off offset:576
	v_lshlrev_b64 v[50:51], 12, v[50:51]
	s_waitcnt vmcnt(4)
	v_pk_fma_f32 v[20:21], v[20:21], v[68:69], v[36:37]
	v_pk_fma_f32 v[18:19], v[18:19], v[66:67], v[34:35]
	v_lshl_add_u64 v[34:35], s[24:25], 0, v[52:53]
	v_lshl_add_u64 v[36:37], s[24:25], 0, v[50:51]
	v_pk_fma_f32 v[32:33], v[32:33], v[80:81], v[48:49]
	v_pk_fma_f32 v[30:31], v[30:31], v[78:79], v[46:47]
	s_and_b64 vcc, exec, s[4:5]
	v_lshl_add_u64 v[34:35], v[34:35], 0, v[180:181]
	v_lshl_add_u64 v[36:37], v[36:37], 0, v[180:181]
	s_mov_b64 s[4:5], -1
	v_pk_fma_f32 v[28:29], v[28:29], v[76:77], v[44:45]
	v_pk_fma_f32 v[26:27], v[26:27], v[74:75], v[42:43]
	v_pk_fma_f32 v[24:25], v[24:25], v[72:73], v[40:41]
	v_pk_fma_f32 v[22:23], v[22:23], v[70:71], v[38:39]
	s_cmp_eq_u32 s100, 1
	s_cselect_b64 exec, 0, -1
	global_store_dwordx4 v[36:37], v[30:33], off
	global_store_dwordx4 v[36:37], v[26:29], off offset:64
	global_store_dwordx4 v[36:37], v[22:25], off offset:512
	global_store_dwordx4 v[36:37], v[18:21], off offset:576
	s_mov_b64 exec, -1
	s_waitcnt vmcnt(7)
	v_pk_fma_f32 v[16:17], v[16:17], v[80:81], v[56:57]
	v_pk_fma_f32 v[14:15], v[14:15], v[78:79], v[54:55]
	s_waitcnt vmcnt(6)
	v_pk_fma_f32 v[12:13], v[12:13], v[76:77], v[60:61]
	v_pk_fma_f32 v[10:11], v[10:11], v[74:75], v[58:59]
	s_waitcnt vmcnt(5)
	v_pk_fma_f32 v[8:9], v[8:9], v[72:73], v[64:65]
	v_pk_fma_f32 v[6:7], v[6:7], v[70:71], v[62:63]
	s_waitcnt vmcnt(4)
	v_pk_fma_f32 v[4:5], v[4:5], v[68:69], v[84:85]
	v_pk_fma_f32 v[2:3], v[2:3], v[66:67], v[82:83]
	s_cmp_eq_u32 s100, 1
	s_cselect_b64 exec, 0, -1
	global_store_dwordx4 v[34:35], v[14:17], off
	global_store_dwordx4 v[34:35], v[10:13], off offset:64
	global_store_dwordx4 v[34:35], v[6:9], off offset:512
	global_store_dwordx4 v[34:35], v[2:5], off offset:576
	s_mov_b64 exec, -1
	s_cbranch_vccnz .LBB0_985
	s_andn2_b64 vcc, exec, s[8:9]
	s_cbranch_vccnz .LBB0_984
	s_barrier
	s_branch .LBB0_984
